# P4 gate-row loads: second batch (last four) issued into the first four quads once consumed -> 15 of 16 loads overlapped
# speedup vs baseline: 1.0048x; 1.0048x over previous
.LBB0_481:
	s_or_b64 exec, exec, s[0:1]
	s_add_u32 s2, s9, s46
	v_and_b32_e32 v146, 16, v146
	s_addc_u32 s4, s8, s47
	s_lshl_b64 s[0:1], s[10:11], 2
	v_cmp_eq_u32_e64 s[36:37], 0, v146
	v_add_u32_e32 v146, 12, v148
	s_add_u32 s0, s2, s0
	v_cndmask_b32_e64 v154, v146, v148, s[36:37]
	v_lshl_add_u32 v146, v0, 2, 0
	s_addc_u32 s1, s4, s1
	v_lshlrev_b32_e32 v18, 2, v148
	v_add_u32_e32 v186, 0x20400, v146
	s_waitcnt lgkmcnt(0)
	s_barrier
	global_load_dwordx4 v[30:33], v18, s[0:1]
	global_load_dwordx4 v[26:29], v18, s[0:1] offset:64
	global_load_dwordx4 v[22:25], v18, s[0:1] offset:128
	s_nop 0
	global_load_dwordx4 v[18:21], v18, s[0:1] offset:192
	ds_read2_b32 v[156:157], v186 offset1:16
	ds_read2_b32 v[158:159], v186 offset0:128 offset1:144
	v_or_b32_e32 v150, s7, v0
	v_mov_b32_e32 v172, 0x3727c5ac
	s_mov_b32 s4, 0xf800000
	s_waitcnt lgkmcnt(1)
	v_add_f32_e32 v0, 0, v156
	s_waitcnt lgkmcnt(0)
	v_add_f32_e32 v0, v0, v158
	v_add_u32_e32 v158, 0x400, v186
	ds_read2_b32 v[160:161], v158 offset1:16
	ds_read2_b32 v[162:163], v158 offset0:128 offset1:144
	v_mov_b32_e32 v173, 0x260
	v_or_b32_e32 v180, s10, v154
	s_addk_i32 s16, 0x3400
	s_waitcnt lgkmcnt(1)
	v_add_f32_e32 v0, v0, v160
	v_add_u32_e32 v160, 0x800, v186
	ds_read2_b32 v[164:165], v160 offset1:16
	s_waitcnt lgkmcnt(1)
	v_add_f32_e32 v0, v0, v162
	ds_read2_b32 v[174:175], v160 offset0:128 offset1:144
	v_add_u32_e32 v162, 0xc00, v186
	ds_read2_b32 v[176:177], v162 offset1:16
	ds_read2_b32 v[178:179], v162 offset0:128 offset1:144
	s_waitcnt lgkmcnt(3)
	v_add_f32_e32 v0, v0, v164
	s_waitcnt lgkmcnt(2)
	v_add_f32_e32 v0, v0, v174
	v_mov_b64_e32 v[152:153], s[44:45]
	s_waitcnt lgkmcnt(1)
	v_add_f32_e32 v0, v0, v176
	s_waitcnt lgkmcnt(0)
	v_add_f32_e32 v0, v0, v178
	v_fmamk_f32 v0, v0, 0x3b000000, v172
	v_cmp_gt_f32_e32 vcc, s4, v0
	v_mul_f32_e32 v146, 0x4f800000, v0
	s_movk_i32 s2, 0x1800
	v_cndmask_b32_e32 v0, v0, v146, vcc
	v_sqrt_f32_e32 v146, v0
	s_lshl_b32 s18, s6, 10
	v_ashrrev_i32_e32 v181, 31, v180
	s_add_i32 s15, s15, s56
	v_add_u32_e32 v147, -1, v146
	v_fma_f32 v148, -v147, v146, v0
	v_cmp_ge_f32_e64 s[0:1], 0, v148
	v_add_u32_e32 v148, 1, v146
	v_mov_b32_e32 v234, 0x3727c5ac
	v_cndmask_b32_e64 v147, v146, v147, s[0:1]
	v_fma_f32 v146, -v148, v146, v0
	v_cmp_lt_f32_e64 s[0:1], 0, v146
	v_mov_b32_e32 v168, 0x260
	s_nop 0
	v_cndmask_b32_e64 v146, v147, v148, s[0:1]
	v_mul_f32_e32 v147, 0x37800000, v146
	v_cndmask_b32_e32 v146, v146, v147, vcc
	v_cmp_class_f32_e32 vcc, v0, v173
	s_nop 1
	v_cndmask_b32_e32 v0, v146, v0, vcc
	v_div_scale_f32 v146, s[0:1], v0, v0, 1.0
	v_rcp_f32_e32 v147, v146
	s_nop 0
	v_fma_f32 v148, -v146, v147, 1.0
	v_fmac_f32_e32 v147, v148, v147
	v_div_scale_f32 v148, vcc, 1.0, v0, 1.0
	v_mul_f32_e32 v149, v148, v147
	v_fma_f32 v151, -v146, v149, v148
	v_fmac_f32_e32 v149, v151, v147
	v_fma_f32 v146, -v146, v149, v148
	v_div_fmas_f32 v146, v146, v147, v149
	v_div_fixup_f32 v156, v146, v0, 1.0
	v_mad_i64_i32 v[148:149], s[0:1], v150, s2, v[152:153]
	v_add_u32_e32 v0, s16, v180
	v_ashrrev_i32_e32 v151, 31, v150
	v_lshl_add_u64 v[182:183], v[148:149], 0, s[18:19]
	v_ashrrev_i32_e32 v148, 8, v0
	v_lshlrev_b64 v[146:147], 9, v[150:151]
	v_ashrrev_i32_e32 v149, 31, v148
	v_mov_b32_e32 v0, s10
	s_movk_i32 s0, 0xdc
	v_lshl_add_u64 v[146:147], s[38:39], 0, v[146:147]
	v_bitop3_b32 v0, v154, s0, v0 bitop3:0xc8
	v_lshlrev_b64 v[154:155], 22, v[148:149]
	v_lshl_add_u64 v[184:185], v[146:147], 0, v[154:155]
	v_lshlrev_b32_e32 v0, 1, v0
	v_lshl_add_u64 v[146:147], v[184:185], 0, v[0:1]
	global_load_dwordx4 v[146:149], v[146:147], off nt
	v_lshl_add_u64 v[232:233], v[184:185], 0, v[0:1]
	s_mov_b32 s78, 0x2000
	s_mov_b32 s79, 0
	global_load_dwordx4 v[188:191], v[232:233], off offset:64 nt
	v_lshl_add_u64 v[232:233], v[232:233], 0, s[78:79]
	global_load_dwordx4 v[192:195], v[232:233], off nt
	global_load_dwordx4 v[196:199], v[232:233], off offset:64 nt
	v_lshl_add_u64 v[232:233], v[232:233], 0, s[78:79]
	global_load_dwordx4 v[200:203], v[232:233], off nt
	global_load_dwordx4 v[204:207], v[232:233], off offset:64 nt
	v_lshl_add_u64 v[232:233], v[232:233], 0, s[78:79]
	global_load_dwordx4 v[208:211], v[232:233], off nt
	global_load_dwordx4 v[212:215], v[232:233], off offset:64 nt
	v_lshl_add_u64 v[232:233], v[232:233], 0, s[78:79]
	global_load_dwordx4 v[216:219], v[232:233], off nt
	global_load_dwordx4 v[220:223], v[232:233], off offset:64 nt
	v_lshl_add_u64 v[232:233], v[232:233], 0, s[78:79]
	global_load_dwordx4 v[224:227], v[232:233], off nt
	global_load_dwordx4 v[228:231], v[232:233], off offset:64 nt
	v_pk_mul_f32 v[140:141], v[140:141], v[156:157] op_sel_hi:[1,0]
	v_pk_mul_f32 v[144:145], v[144:145], v[156:157] op_sel_hi:[1,0]
	s_waitcnt vmcnt(15)
	v_pk_mul_f32 v[140:141], v[32:33], v[140:141]
	s_waitcnt vmcnt(14)
	v_pk_mul_f32 v[144:145], v[28:29], v[144:145]
	v_pk_mul_f32 v[138:139], v[138:139], v[156:157] op_sel_hi:[1,0]
	v_cndmask_b32_e64 v166, v140, v144, s[36:37]
	ds_swizzle_b32 v166, v166 offset:swizzle(SWAP,16)
	v_cndmask_b32_e64 v167, v141, v145, s[36:37]
	ds_swizzle_b32 v167, v167 offset:swizzle(SWAP,16)
	v_pk_mul_f32 v[142:143], v[142:143], v[156:157] op_sel_hi:[1,0]
	v_pk_mul_f32 v[138:139], v[30:31], v[138:139]
	s_waitcnt lgkmcnt(1)
	v_cndmask_b32_e64 v140, v166, v140, s[36:37]
	v_cndmask_b32_e64 v166, v144, v166, s[36:37]
	s_waitcnt lgkmcnt(0)
	v_cndmask_b32_e64 v141, v167, v141, s[36:37]
	v_cndmask_b32_e64 v167, v145, v167, s[36:37]
	v_pk_mul_f32 v[142:143], v[26:27], v[142:143]
	s_movk_i32 s0, 0xfc
	v_cndmask_b32_e64 v151, v138, v142, s[36:37]
	v_cndmask_b32_e64 v164, v139, v143, s[36:37]
	ds_swizzle_b32 v151, v151 offset:swizzle(SWAP,16)
	ds_swizzle_b32 v164, v164 offset:swizzle(SWAP,16)
	v_pk_mul_f32 v[130:131], v[130:131], v[156:157] op_sel_hi:[1,0]
	v_pk_mul_f32 v[134:135], v[134:135], v[156:157] op_sel_hi:[1,0]
	s_waitcnt vmcnt(13)
	v_pk_mul_f32 v[130:131], v[22:23], v[130:131]
	s_waitcnt lgkmcnt(1)
	v_cndmask_b32_e64 v138, v151, v138, s[36:37]
	s_waitcnt lgkmcnt(0)
	v_cndmask_b32_e64 v139, v164, v139, s[36:37]
	v_cndmask_b32_e64 v143, v143, v164, s[36:37]
	v_cndmask_b32_e64 v142, v142, v151, s[36:37]
	s_waitcnt vmcnt(12)
	v_pk_mul_f32 v[134:135], v[18:19], v[134:135]
	v_pk_mul_f32 v[132:133], v[132:133], v[156:157] op_sel_hi:[1,0]
	v_pk_mul_f32 v[136:137], v[136:137], v[156:157] op_sel_hi:[1,0]
	v_pk_mul_f32 v[132:133], v[24:25], v[132:133]
	v_pk_mul_f32 v[136:137], v[20:21], v[136:137]
	s_waitcnt vmcnt(11)
	v_lshlrev_b32_e32 v144, 16, v146
	v_and_b32_e32 v145, 0xffff0000, v146
	v_mul_f32_e32 v146, 0xbfb8aa3b, v144
	v_exp_f32_e32 v146, v146
	v_cndmask_b32_e64 v151, v132, v136, s[36:37]
	v_cndmask_b32_e64 v156, v133, v137, s[36:37]
	ds_swizzle_b32 v151, v151 offset:swizzle(SWAP,16)
	v_add_f32_e32 v146, 1.0, v146
	v_rcp_f32_e32 v170, v146
	v_mul_f32_e32 v146, 0xbfb8aa3b, v145
	v_exp_f32_e32 v146, v146
	ds_swizzle_b32 v156, v156 offset:swizzle(SWAP,16)
	s_waitcnt lgkmcnt(1)
	v_cndmask_b32_e64 v132, v151, v132, s[36:37]
	v_cndmask_b32_e64 v136, v136, v151, s[36:37]
	v_add_f32_e32 v146, 1.0, v146
	v_rcp_f32_e32 v171, v146
	s_waitcnt lgkmcnt(0)
	v_cndmask_b32_e64 v133, v156, v133, s[36:37]
	v_cndmask_b32_e64 v137, v137, v156, s[36:37]
	v_pk_mul_f32 v[144:145], v[170:171], v[144:145]
	s_nop 0
	v_pk_mul_f32 v[138:139], v[144:145], v[138:139]
	s_nop 0
	v_cvt_pk_bf16_f32 v144, v138, v139
	v_lshlrev_b32_e32 v138, 16, v147
	v_mul_f32_e32 v145, 0xbfb8aa3b, v138
	v_exp_f32_e32 v145, v145
	v_and_b32_e32 v139, 0xffff0000, v147
	v_add_f32_e32 v145, 1.0, v145
	v_rcp_f32_e32 v146, v145
	v_mul_f32_e32 v145, 0xbfb8aa3b, v139
	v_exp_f32_e32 v145, v145
	s_nop 0
	v_add_f32_e32 v145, 1.0, v145
	v_rcp_f32_e32 v147, v145
	s_nop 0
	v_pk_mul_f32 v[138:139], v[146:147], v[138:139]
	s_nop 0
	v_pk_mul_f32 v[138:139], v[138:139], v[140:141]
	s_nop 0
	v_cvt_pk_bf16_f32 v145, v138, v139
	v_lshlrev_b32_e32 v138, 16, v148
	v_and_b32_e32 v139, 0xffff0000, v148
	v_mul_f32_e32 v140, 0xbfb8aa3b, v138
	v_mul_f32_e32 v141, 0xbfb8aa3b, v139
	v_exp_f32_e32 v140, v140
	v_exp_f32_e32 v141, v141
	v_cndmask_b32_e64 v148, v130, v134, s[36:37]
	ds_swizzle_b32 v148, v148 offset:swizzle(SWAP,16)
	v_add_f32_e32 v140, 1.0, v140
	v_add_f32_e32 v141, 1.0, v141
	v_rcp_f32_e32 v140, v140
	v_rcp_f32_e32 v141, v141
	s_waitcnt lgkmcnt(0)
	v_cndmask_b32_e64 v130, v148, v130, s[36:37]
	v_cndmask_b32_e64 v134, v134, v148, s[36:37]
	v_pk_mul_f32 v[138:139], v[140:141], v[138:139]
	s_nop 0
	v_pk_mul_f32 v[138:139], v[138:139], v[142:143]
	s_nop 0
	v_cvt_pk_bf16_f32 v146, v138, v139
	v_lshlrev_b32_e32 v138, 16, v149
	v_and_b32_e32 v139, 0xffff0000, v149
	v_mul_f32_e32 v140, 0xbfb8aa3b, v138
	v_mul_f32_e32 v141, 0xbfb8aa3b, v139
	v_exp_f32_e32 v140, v140
	v_exp_f32_e32 v141, v141
	v_cndmask_b32_e64 v149, v131, v135, s[36:37]
	ds_swizzle_b32 v149, v149 offset:swizzle(SWAP,16)
	v_add_f32_e32 v140, 1.0, v140
	v_add_f32_e32 v141, 1.0, v141
	v_rcp_f32_e32 v140, v140
	v_rcp_f32_e32 v141, v141
	s_waitcnt lgkmcnt(0)
	v_cndmask_b32_e64 v131, v149, v131, s[36:37]
	v_cndmask_b32_e64 v135, v135, v149, s[36:37]
	v_pk_mul_f32 v[138:139], v[140:141], v[138:139]
	s_nop 0
	v_pk_mul_f32 v[138:139], v[138:139], v[166:167]
	v_bitop3_b32 v140, v180, s0, 32 bitop3:0xc8
	v_cvt_pk_bf16_f32 v147, v138, v139
	v_lshlrev_b64 v[138:139], 1, v[180:181]
	v_lshl_add_u64 v[142:143], v[182:183], 0, v[138:139]
	v_lshlrev_b32_e32 v140, 1, v140
	v_mov_b32_e32 v141, v1
	global_store_dwordx4 v[142:143], v[144:147], off offset:2048
	s_nop 1
	s_waitcnt vmcnt(11)
	v_lshlrev_b32_e32 v148, 16, v188
	v_and_b32_e32 v149, 0xffff0000, v188
	v_mul_f32_e32 v144, 0xbfb8aa3b, v148
	v_exp_f32_e32 v144, v144
	s_nop 0
	v_add_f32_e32 v144, 1.0, v144
	v_rcp_f32_e32 v166, v144
	v_mul_f32_e32 v144, 0xbfb8aa3b, v149
	v_exp_f32_e32 v144, v144
	s_nop 0
	v_add_f32_e32 v144, 1.0, v144
	v_rcp_f32_e32 v167, v144
	v_lshlrev_b32_e32 v144, 16, v189
	v_and_b32_e32 v145, 0xffff0000, v189
	v_pk_mul_f32 v[148:149], v[166:167], v[148:149]
	s_nop 0
	v_pk_mul_f32 v[130:131], v[148:149], v[130:131]
	s_nop 0
	v_cvt_pk_bf16_f32 v130, v130, v131
	v_mul_f32_e32 v131, 0xbfb8aa3b, v144
	v_exp_f32_e32 v131, v131
	s_nop 0
	v_add_f32_e32 v131, 1.0, v131
	v_rcp_f32_e32 v148, v131
	v_mul_f32_e32 v131, 0xbfb8aa3b, v145
	v_exp_f32_e32 v131, v131
	s_nop 0
	v_add_f32_e32 v131, 1.0, v131
	v_rcp_f32_e32 v149, v131
	s_nop 0
	v_pk_mul_f32 v[144:145], v[148:149], v[144:145]
	s_nop 0
	v_pk_mul_f32 v[132:133], v[144:145], v[132:133]
	s_nop 0
	v_cvt_pk_bf16_f32 v131, v132, v133
	v_lshlrev_b32_e32 v132, 16, v190
	v_and_b32_e32 v133, 0xffff0000, v190
	v_mul_f32_e32 v144, 0xbfb8aa3b, v132
	v_mul_f32_e32 v145, 0xbfb8aa3b, v133
	v_exp_f32_e32 v144, v144
	v_exp_f32_e32 v145, v145
	v_add_f32_e32 v144, 1.0, v144
	v_add_f32_e32 v145, 1.0, v145
	v_rcp_f32_e32 v144, v144
	v_rcp_f32_e32 v145, v145
	s_nop 0
	v_pk_mul_f32 v[132:133], v[144:145], v[132:133]
	s_nop 0
	v_pk_mul_f32 v[132:133], v[132:133], v[134:135]
	v_lshlrev_b32_e32 v134, 16, v191
	v_cvt_pk_bf16_f32 v132, v132, v133
	v_mul_f32_e32 v133, 0xbfb8aa3b, v134
	v_exp_f32_e32 v133, v133
	v_and_b32_e32 v135, 0xffff0000, v191
	v_add_f32_e32 v133, 1.0, v133
	v_rcp_f32_e32 v144, v133
	v_mul_f32_e32 v133, 0xbfb8aa3b, v135
	v_exp_f32_e32 v133, v133
	s_nop 0
	v_add_f32_e32 v133, 1.0, v133
	v_rcp_f32_e32 v145, v133
	s_nop 0
	v_pk_mul_f32 v[134:135], v[144:145], v[134:135]
	s_nop 0
	v_pk_mul_f32 v[134:135], v[134:135], v[136:137]
	s_nop 0
	v_cvt_pk_bf16_f32 v133, v134, v135
	global_store_dwordx4 v[142:143], v[130:133], off offset:2112
	s_nop 1
	v_add_f32_e32 v130, 0, v157
	v_add_f32_e32 v130, v130, v159
	v_add_f32_e32 v130, v130, v161
	v_add_f32_e32 v130, v130, v163
	v_add_f32_e32 v130, v130, v165
	v_add_f32_e32 v130, v130, v175
	v_add_f32_e32 v130, v130, v177
	v_add_f32_e32 v130, v130, v179
	v_fmamk_f32 v130, v130, 0x3b000000, v172
	v_cmp_gt_f32_e32 vcc, s4, v130
	v_mul_f32_e32 v131, 0x4f800000, v130
	s_nop 0
	v_cndmask_b32_e32 v130, v130, v131, vcc
	v_sqrt_f32_e32 v131, v130
	s_nop 0
	v_add_u32_e32 v132, -1, v131
	v_fma_f32 v133, -v132, v131, v130
	v_cmp_ge_f32_e64 s[0:1], 0, v133
	v_add_u32_e32 v133, 1, v131
	s_nop 0
	v_cndmask_b32_e64 v132, v131, v132, s[0:1]
	v_fma_f32 v131, -v133, v131, v130
	v_cmp_lt_f32_e64 s[0:1], 0, v131
	s_nop 1
	v_cndmask_b32_e64 v131, v132, v133, s[0:1]
	v_mul_f32_e32 v132, 0x37800000, v131
	v_cndmask_b32_e32 v131, v131, v132, vcc
	v_cmp_class_f32_e32 vcc, v130, v173
	s_nop 1
	v_cndmask_b32_e32 v130, v131, v130, vcc
	v_div_scale_f32 v131, s[0:1], v130, v130, 1.0
	v_rcp_f32_e32 v132, v131
	s_nop 0
	v_fma_f32 v133, -v131, v132, 1.0
	v_fmac_f32_e32 v132, v133, v132
	v_div_scale_f32 v133, vcc, 1.0, v130, 1.0
	v_mul_f32_e32 v134, v133, v132
	v_fma_f32 v135, -v131, v134, v133
	v_fmac_f32_e32 v134, v135, v132
	v_fma_f32 v131, -v131, v134, v133
	v_div_fmas_f32 v131, v131, v132, v134
	v_div_fixup_f32 v134, v131, v130, 1.0
	v_or_b32_e32 v130, 16, v150
	v_ashrrev_i32_e32 v131, 31, v130
	v_lshlrev_b64 v[132:133], 9, v[130:131]
	v_lshl_add_u64 v[132:133], s[38:39], 0, v[132:133]
	v_mad_i64_i32 v[130:131], s[0:1], v130, s2, v[152:153]
	v_lshl_add_u64 v[142:143], v[132:133], 0, v[154:155]
	v_lshl_add_u64 v[136:137], v[130:131], 0, s[18:19]
	v_pk_mul_f32 v[122:123], v[122:123], v[134:135] op_sel_hi:[1,0]
	v_pk_mul_f32 v[126:127], v[126:127], v[134:135] op_sel_hi:[1,0]
	v_pk_mul_f32 v[124:125], v[124:125], v[134:135] op_sel_hi:[1,0]
	v_pk_mul_f32 v[122:123], v[30:31], v[122:123]
	v_pk_mul_f32 v[128:129], v[128:129], v[134:135] op_sel_hi:[1,0]
	v_pk_mul_f32 v[126:127], v[26:27], v[126:127]
	v_pk_mul_f32 v[124:125], v[32:33], v[124:125]
	v_pk_mul_f32 v[128:129], v[28:29], v[128:129]
	v_cndmask_b32_e64 v144, v123, v127, s[36:37]
	ds_swizzle_b32 v146, v144 offset:swizzle(SWAP,16)
	v_cndmask_b32_e64 v144, v124, v128, s[36:37]
	ds_swizzle_b32 v147, v144 offset:swizzle(SWAP,16)
	v_cndmask_b32_e64 v144, v125, v129, s[36:37]
	ds_swizzle_b32 v148, v144 offset:swizzle(SWAP,16)
	s_waitcnt lgkmcnt(2)
	v_cndmask_b32_e64 v123, v146, v123, s[36:37]
	v_cndmask_b32_e64 v127, v127, v146, s[36:37]
	s_waitcnt lgkmcnt(1)
	v_cndmask_b32_e64 v144, v147, v124, s[36:37]
	v_cndmask_b32_e64 v135, v122, v126, s[36:37]
	s_waitcnt lgkmcnt(0)
	v_cndmask_b32_e64 v145, v148, v125, s[36:37]
	ds_swizzle_b32 v135, v135 offset:swizzle(SWAP,16)
	v_cndmask_b32_e64 v128, v128, v147, s[36:37]
	v_cndmask_b32_e64 v129, v129, v148, s[36:37]
	s_waitcnt lgkmcnt(0)
	v_cndmask_b32_e64 v122, v135, v122, s[36:37]
	v_cndmask_b32_e64 v126, v126, v135, s[36:37]
	v_pk_mul_f32 v[114:115], v[114:115], v[134:135] op_sel_hi:[1,0]
	v_pk_mul_f32 v[118:119], v[118:119], v[134:135] op_sel_hi:[1,0]
	v_pk_mul_f32 v[114:115], v[22:23], v[114:115]
	v_pk_mul_f32 v[118:119], v[18:19], v[118:119]
	v_pk_mul_f32 v[116:117], v[116:117], v[134:135] op_sel_hi:[1,0]
	v_pk_mul_f32 v[120:121], v[120:121], v[134:135] op_sel_hi:[1,0]
	v_pk_mul_f32 v[116:117], v[24:25], v[116:117]
	v_pk_mul_f32 v[120:121], v[20:21], v[120:121]
	s_waitcnt vmcnt(11)
	v_lshlrev_b32_e32 v124, 16, v192
	v_and_b32_e32 v125, 0xffff0000, v192
	v_mul_f32_e32 v130, 0xbfb8aa3b, v124
	v_exp_f32_e32 v130, v130
	s_nop 0
	v_add_f32_e32 v130, 1.0, v130
	v_rcp_f32_e32 v146, v130
	v_mul_f32_e32 v130, 0xbfb8aa3b, v125
	v_exp_f32_e32 v130, v130
	s_nop 0
	v_add_f32_e32 v130, 1.0, v130
	v_rcp_f32_e32 v147, v130
	s_nop 0
	v_pk_mul_f32 v[124:125], v[146:147], v[124:125]
	s_nop 0
	v_pk_mul_f32 v[122:123], v[124:125], v[122:123]
	s_nop 0
	v_cvt_pk_bf16_f32 v124, v122, v123
	v_lshlrev_b32_e32 v122, 16, v193
	v_mul_f32_e32 v125, 0xbfb8aa3b, v122
	v_exp_f32_e32 v125, v125
	v_and_b32_e32 v123, 0xffff0000, v193
	v_add_f32_e32 v125, 1.0, v125
	v_rcp_f32_e32 v130, v125
	v_mul_f32_e32 v125, 0xbfb8aa3b, v123
	v_exp_f32_e32 v125, v125
	s_nop 0
	v_add_f32_e32 v125, 1.0, v125
	v_rcp_f32_e32 v131, v125
	s_nop 0
	v_pk_mul_f32 v[122:123], v[130:131], v[122:123]
	s_nop 0
	v_pk_mul_f32 v[122:123], v[122:123], v[144:145]
	s_nop 0
	v_cvt_pk_bf16_f32 v125, v122, v123
	v_lshlrev_b32_e32 v122, 16, v194
	v_and_b32_e32 v123, 0xffff0000, v194
	v_mul_f32_e32 v130, 0xbfb8aa3b, v122
	v_mul_f32_e32 v131, 0xbfb8aa3b, v123
	v_exp_f32_e32 v130, v130
	v_exp_f32_e32 v131, v131
	v_add_f32_e32 v130, 1.0, v130
	v_add_f32_e32 v131, 1.0, v131
	v_rcp_f32_e32 v130, v130
	v_rcp_f32_e32 v131, v131
	s_nop 0
	v_pk_mul_f32 v[122:123], v[130:131], v[122:123]
	s_nop 0
	v_pk_mul_f32 v[122:123], v[122:123], v[126:127]
	s_nop 0
	v_cvt_pk_bf16_f32 v126, v122, v123
	v_lshlrev_b32_e32 v122, 16, v195
	v_mul_f32_e32 v127, 0xbfb8aa3b, v122
	v_exp_f32_e32 v127, v127
	v_and_b32_e32 v123, 0xffff0000, v195
	ds_read2_b32 v[132:133], v162 offset0:160 offset1:176
	v_add_f32_e32 v127, 1.0, v127
	v_rcp_f32_e32 v130, v127
	v_mul_f32_e32 v127, 0xbfb8aa3b, v123
	v_exp_f32_e32 v127, v127
	s_nop 0
	v_add_f32_e32 v127, 1.0, v127
	v_rcp_f32_e32 v131, v127
	s_nop 0
	v_pk_mul_f32 v[122:123], v[130:131], v[122:123]
	s_nop 0
	v_pk_mul_f32 v[122:123], v[122:123], v[128:129]
	v_cndmask_b32_e64 v128, v114, v118, s[36:37]
	v_cvt_pk_bf16_f32 v127, v122, v123
	v_lshl_add_u64 v[122:123], v[136:137], 0, v[138:139]
	global_store_dwordx4 v[122:123], v[124:127], off offset:2048
	ds_swizzle_b32 v128, v128 offset:swizzle(SWAP,16)
	v_cndmask_b32_e64 v129, v115, v119, s[36:37]
	ds_swizzle_b32 v129, v129 offset:swizzle(SWAP,16)
	s_waitcnt lgkmcnt(1)
	v_cndmask_b32_e64 v114, v128, v114, s[36:37]
	v_cndmask_b32_e64 v118, v118, v128, s[36:37]
	v_cndmask_b32_e64 v130, v116, v120, s[36:37]
	ds_swizzle_b32 v130, v130 offset:swizzle(SWAP,16)
	s_waitcnt lgkmcnt(1)
	v_cndmask_b32_e64 v115, v129, v115, s[36:37]
	v_cndmask_b32_e64 v119, v119, v129, s[36:37]
	v_cndmask_b32_e64 v131, v117, v121, s[36:37]
	ds_swizzle_b32 v131, v131 offset:swizzle(SWAP,16)
	s_waitcnt lgkmcnt(1)
	v_cndmask_b32_e64 v116, v130, v116, s[36:37]
	v_cndmask_b32_e64 v120, v120, v130, s[36:37]
	s_waitcnt lgkmcnt(0)
	v_cndmask_b32_e64 v117, v131, v117, s[36:37]
	v_cndmask_b32_e64 v121, v121, v131, s[36:37]
	s_waitcnt vmcnt(11)
	v_lshlrev_b32_e32 v128, 16, v196
	v_and_b32_e32 v129, 0xffff0000, v196
	v_mul_f32_e32 v124, 0xbfb8aa3b, v128
	v_exp_f32_e32 v124, v124
	s_nop 0
	v_add_f32_e32 v124, 1.0, v124
	v_rcp_f32_e32 v130, v124
	v_mul_f32_e32 v124, 0xbfb8aa3b, v129
	v_exp_f32_e32 v124, v124
	s_nop 0
	v_add_f32_e32 v124, 1.0, v124
	v_rcp_f32_e32 v131, v124
	v_lshlrev_b32_e32 v124, 16, v197
	v_and_b32_e32 v125, 0xffff0000, v197
	v_pk_mul_f32 v[128:129], v[130:131], v[128:129]
	s_nop 0
	v_pk_mul_f32 v[114:115], v[128:129], v[114:115]
	ds_read2_b32 v[130:131], v162 offset0:32 offset1:48
	v_cvt_pk_bf16_f32 v114, v114, v115
	v_mul_f32_e32 v115, 0xbfb8aa3b, v124
	v_exp_f32_e32 v115, v115
	s_nop 0
	v_add_f32_e32 v115, 1.0, v115
	v_rcp_f32_e32 v128, v115
	v_mul_f32_e32 v115, 0xbfb8aa3b, v125
	v_exp_f32_e32 v115, v115
	s_nop 0
	v_add_f32_e32 v115, 1.0, v115
	v_rcp_f32_e32 v129, v115
	s_nop 0
	v_pk_mul_f32 v[124:125], v[128:129], v[124:125]
	s_nop 0
	v_pk_mul_f32 v[116:117], v[124:125], v[116:117]
	ds_read2_b32 v[128:129], v160 offset0:160 offset1:176
	v_cvt_pk_bf16_f32 v115, v116, v117
	v_lshlrev_b32_e32 v116, 16, v198
	v_and_b32_e32 v117, 0xffff0000, v198
	v_mul_f32_e32 v124, 0xbfb8aa3b, v116
	v_mul_f32_e32 v125, 0xbfb8aa3b, v117
	v_exp_f32_e32 v124, v124
	v_exp_f32_e32 v125, v125
	v_add_f32_e32 v124, 1.0, v124
	v_add_f32_e32 v125, 1.0, v125
	v_rcp_f32_e32 v124, v124
	v_rcp_f32_e32 v125, v125
	s_nop 0
	v_pk_mul_f32 v[116:117], v[124:125], v[116:117]
	s_nop 0
	v_pk_mul_f32 v[116:117], v[116:117], v[118:119]
	v_lshlrev_b32_e32 v118, 16, v199
	v_cvt_pk_bf16_f32 v116, v116, v117
	v_mul_f32_e32 v117, 0xbfb8aa3b, v118
	v_exp_f32_e32 v117, v117
	v_and_b32_e32 v119, 0xffff0000, v199
	ds_read2_b32 v[126:127], v160 offset0:32 offset1:48
	v_add_f32_e32 v117, 1.0, v117
	v_rcp_f32_e32 v124, v117
	v_mul_f32_e32 v117, 0xbfb8aa3b, v119
	v_exp_f32_e32 v117, v117
	s_nop 0
	v_add_f32_e32 v117, 1.0, v117
	v_rcp_f32_e32 v125, v117
	s_nop 0
	v_pk_mul_f32 v[118:119], v[124:125], v[118:119]
	s_nop 0
	v_pk_mul_f32 v[118:119], v[118:119], v[120:121]
	ds_read2_b32 v[120:121], v186 offset0:160 offset1:176
	v_cvt_pk_bf16_f32 v117, v118, v119
	ds_read2_b32 v[118:119], v186 offset0:32 offset1:48
	global_store_dwordx4 v[122:123], v[114:117], off offset:2112
	ds_read2_b32 v[122:123], v158 offset0:32 offset1:48
	ds_read2_b32 v[124:125], v158 offset0:160 offset1:176
	s_waitcnt lgkmcnt(2)
	v_add_f32_e32 v114, 0, v118
	v_add_f32_e32 v114, v114, v120
	s_waitcnt lgkmcnt(1)
	v_add_f32_e32 v114, v114, v122
	s_waitcnt lgkmcnt(0)
	v_add_f32_e32 v114, v114, v124
	v_add_f32_e32 v114, v114, v126
	v_add_f32_e32 v114, v114, v128
	v_add_f32_e32 v114, v114, v130
	v_add_f32_e32 v114, v114, v132
	v_fmamk_f32 v114, v114, 0x3b000000, v172
	v_cmp_gt_f32_e32 vcc, s4, v114
	v_mul_f32_e32 v115, 0x4f800000, v114
	s_nop 0
	v_cndmask_b32_e32 v114, v114, v115, vcc
	v_sqrt_f32_e32 v115, v114
	s_nop 0
	v_add_u32_e32 v116, -1, v115
	v_fma_f32 v117, -v116, v115, v114
	v_cmp_ge_f32_e64 s[0:1], 0, v117
	v_add_u32_e32 v117, 1, v115
	s_nop 0
	v_cndmask_b32_e64 v116, v115, v116, s[0:1]
	v_fma_f32 v115, -v117, v115, v114
	v_cmp_lt_f32_e64 s[0:1], 0, v115
	s_nop 1
	v_cndmask_b32_e64 v115, v116, v117, s[0:1]
	v_mul_f32_e32 v116, 0x37800000, v115
	v_cndmask_b32_e32 v115, v115, v116, vcc
	v_cmp_class_f32_e32 vcc, v114, v173
	s_nop 1
	v_cndmask_b32_e32 v114, v115, v114, vcc
	v_div_scale_f32 v115, s[0:1], v114, v114, 1.0
	v_rcp_f32_e32 v116, v115
	s_nop 0
	v_fma_f32 v117, -v115, v116, 1.0
	v_fmac_f32_e32 v116, v117, v116
	v_div_scale_f32 v117, vcc, 1.0, v114, 1.0
	v_mul_f32_e32 v118, v117, v116
	v_fma_f32 v120, -v115, v118, v117
	v_fmac_f32_e32 v118, v120, v116
	v_fma_f32 v115, -v115, v118, v117
	v_div_fmas_f32 v115, v115, v116, v118
	v_div_fixup_f32 v118, v115, v114, 1.0
	v_or_b32_e32 v114, 32, v150
	v_ashrrev_i32_e32 v115, 31, v114
	v_lshlrev_b64 v[116:117], 9, v[114:115]
	v_lshl_add_u64 v[116:117], s[38:39], 0, v[116:117]
	v_mad_i64_i32 v[114:115], s[0:1], v114, s2, v[152:153]
	v_lshl_add_u64 v[136:137], v[116:117], 0, v[154:155]
	v_lshl_add_u64 v[134:135], v[114:115], 0, s[18:19]
	v_pk_mul_f32 v[108:109], v[108:109], v[118:119] op_sel_hi:[1,0]
	v_pk_mul_f32 v[112:113], v[112:113], v[118:119] op_sel_hi:[1,0]
	v_pk_mul_f32 v[108:109], v[32:33], v[108:109]
	v_pk_mul_f32 v[112:113], v[28:29], v[112:113]
	v_pk_mul_f32 v[106:107], v[106:107], v[118:119] op_sel_hi:[1,0]
	v_cndmask_b32_e64 v124, v108, v112, s[36:37]
	ds_swizzle_b32 v124, v124 offset:swizzle(SWAP,16)
	v_cndmask_b32_e64 v126, v109, v113, s[36:37]
	ds_swizzle_b32 v126, v126 offset:swizzle(SWAP,16)
	v_pk_mul_f32 v[110:111], v[110:111], v[118:119] op_sel_hi:[1,0]
	v_pk_mul_f32 v[106:107], v[30:31], v[106:107]
	s_waitcnt lgkmcnt(1)
	v_cndmask_b32_e64 v142, v124, v108, s[36:37]
	v_pk_mul_f32 v[110:111], v[26:27], v[110:111]
	s_waitcnt lgkmcnt(0)
	v_cndmask_b32_e64 v143, v126, v109, s[36:37]
	v_cndmask_b32_e64 v120, v106, v110, s[36:37]
	v_cndmask_b32_e64 v122, v107, v111, s[36:37]
	ds_swizzle_b32 v120, v120 offset:swizzle(SWAP,16)
	ds_swizzle_b32 v122, v122 offset:swizzle(SWAP,16)
	v_cndmask_b32_e64 v113, v113, v126, s[36:37]
	v_cndmask_b32_e64 v112, v112, v124, s[36:37]
	v_pk_mul_f32 v[98:99], v[98:99], v[118:119] op_sel_hi:[1,0]
	s_waitcnt lgkmcnt(1)
	v_cndmask_b32_e64 v106, v120, v106, s[36:37]
	s_waitcnt lgkmcnt(0)
	v_cndmask_b32_e64 v107, v122, v107, s[36:37]
	v_cndmask_b32_e64 v111, v111, v122, s[36:37]
	v_cndmask_b32_e64 v110, v110, v120, s[36:37]
	v_pk_mul_f32 v[102:103], v[102:103], v[118:119] op_sel_hi:[1,0]
	v_pk_mul_f32 v[98:99], v[22:23], v[98:99]
	v_pk_mul_f32 v[102:103], v[18:19], v[102:103]
	v_pk_mul_f32 v[100:101], v[100:101], v[118:119] op_sel_hi:[1,0]
	v_pk_mul_f32 v[104:105], v[104:105], v[118:119] op_sel_hi:[1,0]
	v_pk_mul_f32 v[100:101], v[24:25], v[100:101]
	v_pk_mul_f32 v[104:105], v[20:21], v[104:105]
	s_waitcnt vmcnt(11)
	v_lshlrev_b32_e32 v108, 16, v200
	v_and_b32_e32 v109, 0xffff0000, v200
	v_mul_f32_e32 v114, 0xbfb8aa3b, v108
	v_exp_f32_e32 v114, v114
	s_nop 0
	v_add_f32_e32 v114, 1.0, v114
	v_rcp_f32_e32 v144, v114
	v_mul_f32_e32 v114, 0xbfb8aa3b, v109
	v_exp_f32_e32 v114, v114
	s_nop 0
	v_add_f32_e32 v114, 1.0, v114
	v_rcp_f32_e32 v145, v114
	s_nop 0
	v_pk_mul_f32 v[108:109], v[144:145], v[108:109]
	s_nop 0
	v_pk_mul_f32 v[106:107], v[108:109], v[106:107]
	s_nop 0
	v_cvt_pk_bf16_f32 v108, v106, v107
	v_lshlrev_b32_e32 v106, 16, v201
	v_mul_f32_e32 v109, 0xbfb8aa3b, v106
	v_exp_f32_e32 v109, v109
	v_and_b32_e32 v107, 0xffff0000, v201
	v_add_f32_e32 v109, 1.0, v109
	v_rcp_f32_e32 v114, v109
	v_mul_f32_e32 v109, 0xbfb8aa3b, v107
	v_exp_f32_e32 v109, v109
	s_nop 0
	v_add_f32_e32 v109, 1.0, v109
	v_rcp_f32_e32 v115, v109
	s_nop 0
	v_pk_mul_f32 v[106:107], v[114:115], v[106:107]
	s_nop 0
	v_pk_mul_f32 v[106:107], v[106:107], v[142:143]
	s_nop 0
	v_cvt_pk_bf16_f32 v109, v106, v107
	v_lshlrev_b32_e32 v106, 16, v202
	v_and_b32_e32 v107, 0xffff0000, v202
	v_mul_f32_e32 v114, 0xbfb8aa3b, v106
	v_mul_f32_e32 v115, 0xbfb8aa3b, v107
	v_exp_f32_e32 v114, v114
	v_exp_f32_e32 v115, v115
	v_add_f32_e32 v114, 1.0, v114
	v_add_f32_e32 v115, 1.0, v115
	v_rcp_f32_e32 v114, v114
	v_rcp_f32_e32 v115, v115
	s_nop 0
	v_pk_mul_f32 v[106:107], v[114:115], v[106:107]
	s_nop 0
	v_pk_mul_f32 v[106:107], v[106:107], v[110:111]
	s_nop 0
	v_cvt_pk_bf16_f32 v110, v106, v107
	v_lshlrev_b32_e32 v106, 16, v203
	v_mul_f32_e32 v111, 0xbfb8aa3b, v106
	v_exp_f32_e32 v111, v111
	v_and_b32_e32 v107, 0xffff0000, v203
	v_add_f32_e32 v111, 1.0, v111
	v_rcp_f32_e32 v114, v111
	v_mul_f32_e32 v111, 0xbfb8aa3b, v107
	v_exp_f32_e32 v111, v111
	s_nop 0
	v_add_f32_e32 v111, 1.0, v111
	v_rcp_f32_e32 v115, v111
	s_nop 0
	v_pk_mul_f32 v[106:107], v[114:115], v[106:107]
	s_nop 0
	v_pk_mul_f32 v[106:107], v[106:107], v[112:113]
	v_cndmask_b32_e64 v112, v98, v102, s[36:37]
	v_cvt_pk_bf16_f32 v111, v106, v107
	v_lshl_add_u64 v[106:107], v[134:135], 0, v[138:139]
	global_store_dwordx4 v[106:107], v[108:111], off offset:2048
	ds_swizzle_b32 v112, v112 offset:swizzle(SWAP,16)
	v_cndmask_b32_e64 v113, v99, v103, s[36:37]
	ds_swizzle_b32 v113, v113 offset:swizzle(SWAP,16)
	s_waitcnt lgkmcnt(1)
	v_cndmask_b32_e64 v98, v112, v98, s[36:37]
	v_cndmask_b32_e64 v102, v102, v112, s[36:37]
	v_cndmask_b32_e64 v114, v100, v104, s[36:37]
	ds_swizzle_b32 v114, v114 offset:swizzle(SWAP,16)
	s_waitcnt lgkmcnt(1)
	v_cndmask_b32_e64 v99, v113, v99, s[36:37]
	v_cndmask_b32_e64 v103, v103, v113, s[36:37]
	v_cndmask_b32_e64 v115, v101, v105, s[36:37]
	ds_swizzle_b32 v115, v115 offset:swizzle(SWAP,16)
	s_waitcnt lgkmcnt(1)
	v_cndmask_b32_e64 v100, v114, v100, s[36:37]
	v_cndmask_b32_e64 v104, v104, v114, s[36:37]
	s_waitcnt lgkmcnt(0)
	v_cndmask_b32_e64 v101, v115, v101, s[36:37]
	v_cndmask_b32_e64 v105, v105, v115, s[36:37]
	s_waitcnt vmcnt(11)
	v_lshlrev_b32_e32 v112, 16, v204
	v_and_b32_e32 v113, 0xffff0000, v204
	v_mul_f32_e32 v108, 0xbfb8aa3b, v112
	v_exp_f32_e32 v108, v108
	s_nop 0
	v_add_f32_e32 v108, 1.0, v108
	v_rcp_f32_e32 v114, v108
	v_mul_f32_e32 v108, 0xbfb8aa3b, v113
	v_exp_f32_e32 v108, v108
	s_nop 0
	v_add_f32_e32 v108, 1.0, v108
	v_rcp_f32_e32 v115, v108
	v_lshlrev_b32_e32 v108, 16, v205
	v_and_b32_e32 v109, 0xffff0000, v205
	v_pk_mul_f32 v[112:113], v[114:115], v[112:113]
	s_nop 0
	v_pk_mul_f32 v[98:99], v[112:113], v[98:99]
	s_nop 0
	v_cvt_pk_bf16_f32 v98, v98, v99
	v_mul_f32_e32 v99, 0xbfb8aa3b, v108
	v_exp_f32_e32 v99, v99
	s_nop 0
	v_add_f32_e32 v99, 1.0, v99
	v_rcp_f32_e32 v112, v99
	v_mul_f32_e32 v99, 0xbfb8aa3b, v109
	v_exp_f32_e32 v99, v99
	s_nop 0
	v_add_f32_e32 v99, 1.0, v99
	v_rcp_f32_e32 v113, v99
	s_nop 0
	v_pk_mul_f32 v[108:109], v[112:113], v[108:109]
	s_nop 0
	v_pk_mul_f32 v[100:101], v[108:109], v[100:101]
	s_nop 0
	v_cvt_pk_bf16_f32 v99, v100, v101
	v_lshlrev_b32_e32 v100, 16, v206
	v_and_b32_e32 v101, 0xffff0000, v206
	v_mul_f32_e32 v108, 0xbfb8aa3b, v100
	v_mul_f32_e32 v109, 0xbfb8aa3b, v101
	v_exp_f32_e32 v108, v108
	v_exp_f32_e32 v109, v109
	v_add_f32_e32 v108, 1.0, v108
	v_add_f32_e32 v109, 1.0, v109
	v_rcp_f32_e32 v108, v108
	v_rcp_f32_e32 v109, v109
	s_nop 0
	v_pk_mul_f32 v[100:101], v[108:109], v[100:101]
	s_nop 0
	v_pk_mul_f32 v[100:101], v[100:101], v[102:103]
	v_lshlrev_b32_e32 v102, 16, v207
	v_cvt_pk_bf16_f32 v100, v100, v101
	v_mul_f32_e32 v101, 0xbfb8aa3b, v102
	v_exp_f32_e32 v101, v101
	v_and_b32_e32 v103, 0xffff0000, v207
	v_add_f32_e32 v101, 1.0, v101
	v_rcp_f32_e32 v108, v101
	v_mul_f32_e32 v101, 0xbfb8aa3b, v103
	v_exp_f32_e32 v101, v101
	s_nop 0
	v_add_f32_e32 v101, 1.0, v101
	v_rcp_f32_e32 v109, v101
	s_nop 0
	v_pk_mul_f32 v[102:103], v[108:109], v[102:103]
	s_nop 0
	v_pk_mul_f32 v[102:103], v[102:103], v[104:105]
	s_nop 0
	v_cvt_pk_bf16_f32 v101, v102, v103
	global_store_dwordx4 v[106:107], v[98:101], off offset:2112
	s_nop 1
	v_add_f32_e32 v98, 0, v119
	v_add_f32_e32 v98, v98, v121
	v_add_f32_e32 v98, v98, v123
	v_add_f32_e32 v98, v98, v125
	v_add_f32_e32 v98, v98, v127
	v_add_f32_e32 v98, v98, v129
	v_add_f32_e32 v98, v98, v131
	v_add_f32_e32 v98, v98, v133
	v_fmamk_f32 v98, v98, 0x3b000000, v172
	v_cmp_gt_f32_e32 vcc, s4, v98
	v_mul_f32_e32 v99, 0x4f800000, v98
	s_nop 0
	v_cndmask_b32_e32 v98, v98, v99, vcc
	v_sqrt_f32_e32 v99, v98
	s_nop 0
	v_add_u32_e32 v100, -1, v99
	v_fma_f32 v101, -v100, v99, v98
	v_cmp_ge_f32_e64 s[0:1], 0, v101
	v_add_u32_e32 v101, 1, v99
	s_nop 0
	v_cndmask_b32_e64 v100, v99, v100, s[0:1]
	v_fma_f32 v99, -v101, v99, v98
	v_cmp_lt_f32_e64 s[0:1], 0, v99
	s_nop 1
	v_cndmask_b32_e64 v99, v100, v101, s[0:1]
	v_mul_f32_e32 v100, 0x37800000, v99
	v_cndmask_b32_e32 v99, v99, v100, vcc
	v_cmp_class_f32_e32 vcc, v98, v173
	s_nop 1
	v_cndmask_b32_e32 v98, v99, v98, vcc
	v_div_scale_f32 v99, s[0:1], v98, v98, 1.0
	v_rcp_f32_e32 v100, v99
	s_nop 0
	v_fma_f32 v101, -v99, v100, 1.0
	v_fmac_f32_e32 v100, v101, v100
	v_div_scale_f32 v101, vcc, 1.0, v98, 1.0
	v_mul_f32_e32 v102, v101, v100
	v_fma_f32 v103, -v99, v102, v101
	v_fmac_f32_e32 v102, v103, v100
	v_fma_f32 v99, -v99, v102, v101
	v_div_fmas_f32 v99, v99, v100, v102
	v_div_fixup_f32 v102, v99, v98, 1.0
	v_or_b32_e32 v98, 48, v150
	v_ashrrev_i32_e32 v99, 31, v98
	v_lshlrev_b64 v[100:101], 9, v[98:99]
	v_lshl_add_u64 v[100:101], s[38:39], 0, v[100:101]
	v_mad_i64_i32 v[98:99], s[0:1], v98, s2, v[152:153]
	v_lshl_add_u64 v[106:107], v[100:101], 0, v[154:155]
	v_lshl_add_u64 v[104:105], v[98:99], 0, s[18:19]
	v_pk_mul_f32 v[90:91], v[90:91], v[102:103] op_sel_hi:[1,0]
	v_pk_mul_f32 v[94:95], v[94:95], v[102:103] op_sel_hi:[1,0]
	v_pk_mul_f32 v[92:93], v[92:93], v[102:103] op_sel_hi:[1,0]
	v_pk_mul_f32 v[90:91], v[30:31], v[90:91]
	v_pk_mul_f32 v[96:97], v[96:97], v[102:103] op_sel_hi:[1,0]
	v_pk_mul_f32 v[94:95], v[26:27], v[94:95]
	v_pk_mul_f32 v[92:93], v[32:33], v[92:93]
	v_pk_mul_f32 v[96:97], v[28:29], v[96:97]
	v_cndmask_b32_e64 v108, v91, v95, s[36:37]
	ds_swizzle_b32 v110, v108 offset:swizzle(SWAP,16)
	v_cndmask_b32_e64 v108, v92, v96, s[36:37]
	ds_swizzle_b32 v111, v108 offset:swizzle(SWAP,16)
	v_cndmask_b32_e64 v108, v93, v97, s[36:37]
	ds_swizzle_b32 v112, v108 offset:swizzle(SWAP,16)
	s_waitcnt lgkmcnt(2)
	v_cndmask_b32_e64 v91, v110, v91, s[36:37]
	v_cndmask_b32_e64 v95, v95, v110, s[36:37]
	s_waitcnt lgkmcnt(1)
	v_cndmask_b32_e64 v108, v111, v92, s[36:37]
	v_cndmask_b32_e64 v103, v90, v94, s[36:37]
	s_waitcnt lgkmcnt(0)
	v_cndmask_b32_e64 v109, v112, v93, s[36:37]
	ds_swizzle_b32 v103, v103 offset:swizzle(SWAP,16)
	v_cndmask_b32_e64 v96, v96, v111, s[36:37]
	v_cndmask_b32_e64 v97, v97, v112, s[36:37]
	s_waitcnt lgkmcnt(0)
	v_cndmask_b32_e64 v90, v103, v90, s[36:37]
	v_cndmask_b32_e64 v94, v94, v103, s[36:37]
	v_pk_mul_f32 v[82:83], v[82:83], v[102:103] op_sel_hi:[1,0]
	v_pk_mul_f32 v[86:87], v[86:87], v[102:103] op_sel_hi:[1,0]
	v_pk_mul_f32 v[82:83], v[22:23], v[82:83]
	v_pk_mul_f32 v[86:87], v[18:19], v[86:87]
	v_pk_mul_f32 v[84:85], v[84:85], v[102:103] op_sel_hi:[1,0]
	v_pk_mul_f32 v[88:89], v[88:89], v[102:103] op_sel_hi:[1,0]
	v_pk_mul_f32 v[84:85], v[24:25], v[84:85]
	v_pk_mul_f32 v[88:89], v[20:21], v[88:89]
	s_waitcnt vmcnt(11)
	v_lshlrev_b32_e32 v92, 16, v208
	v_and_b32_e32 v93, 0xffff0000, v208
	v_mul_f32_e32 v98, 0xbfb8aa3b, v92
	v_exp_f32_e32 v98, v98
	s_nop 0
	v_add_f32_e32 v98, 1.0, v98
	v_rcp_f32_e32 v110, v98
	v_mul_f32_e32 v98, 0xbfb8aa3b, v93
	v_exp_f32_e32 v98, v98
	s_nop 0
	v_add_f32_e32 v98, 1.0, v98
	v_rcp_f32_e32 v111, v98
	s_nop 0
	v_pk_mul_f32 v[92:93], v[110:111], v[92:93]
	s_nop 0
	v_pk_mul_f32 v[90:91], v[92:93], v[90:91]
	s_nop 0
	v_cvt_pk_bf16_f32 v92, v90, v91
	v_lshlrev_b32_e32 v90, 16, v209
	v_mul_f32_e32 v93, 0xbfb8aa3b, v90
	v_exp_f32_e32 v93, v93
	v_and_b32_e32 v91, 0xffff0000, v209
	v_add_f32_e32 v93, 1.0, v93
	v_rcp_f32_e32 v98, v93
	v_mul_f32_e32 v93, 0xbfb8aa3b, v91
	v_exp_f32_e32 v93, v93
	s_nop 0
	v_add_f32_e32 v93, 1.0, v93
	v_rcp_f32_e32 v99, v93
	s_nop 0
	v_pk_mul_f32 v[90:91], v[98:99], v[90:91]
	s_nop 0
	v_pk_mul_f32 v[90:91], v[90:91], v[108:109]
	s_nop 0
	v_cvt_pk_bf16_f32 v93, v90, v91
	v_lshlrev_b32_e32 v90, 16, v210
	v_and_b32_e32 v91, 0xffff0000, v210
	v_mul_f32_e32 v98, 0xbfb8aa3b, v90
	v_mul_f32_e32 v99, 0xbfb8aa3b, v91
	v_exp_f32_e32 v98, v98
	v_exp_f32_e32 v99, v99
	v_add_f32_e32 v98, 1.0, v98
	v_add_f32_e32 v99, 1.0, v99
	v_rcp_f32_e32 v98, v98
	v_rcp_f32_e32 v99, v99
	s_nop 0
	v_pk_mul_f32 v[90:91], v[98:99], v[90:91]
	s_nop 0
	v_pk_mul_f32 v[90:91], v[90:91], v[94:95]
	s_nop 0
	v_cvt_pk_bf16_f32 v94, v90, v91
	v_lshlrev_b32_e32 v90, 16, v211
	v_mul_f32_e32 v95, 0xbfb8aa3b, v90
	v_exp_f32_e32 v95, v95
	v_and_b32_e32 v91, 0xffff0000, v211
	ds_read2_b32 v[100:101], v162 offset0:192 offset1:208
	v_add_f32_e32 v95, 1.0, v95
	v_rcp_f32_e32 v98, v95
	v_mul_f32_e32 v95, 0xbfb8aa3b, v91
	v_exp_f32_e32 v95, v95
	s_nop 0
	v_add_f32_e32 v95, 1.0, v95
	v_rcp_f32_e32 v99, v95
	s_nop 0
	v_pk_mul_f32 v[90:91], v[98:99], v[90:91]
	s_nop 0
	v_pk_mul_f32 v[90:91], v[90:91], v[96:97]
	v_cndmask_b32_e64 v96, v82, v86, s[36:37]
	v_cvt_pk_bf16_f32 v95, v90, v91
	v_lshl_add_u64 v[90:91], v[104:105], 0, v[138:139]
	global_store_dwordx4 v[90:91], v[92:95], off offset:2048
	ds_swizzle_b32 v96, v96 offset:swizzle(SWAP,16)
	v_cndmask_b32_e64 v97, v83, v87, s[36:37]
	ds_swizzle_b32 v97, v97 offset:swizzle(SWAP,16)
	s_waitcnt lgkmcnt(1)
	v_cndmask_b32_e64 v82, v96, v82, s[36:37]
	v_cndmask_b32_e64 v86, v86, v96, s[36:37]
	v_cndmask_b32_e64 v98, v84, v88, s[36:37]
	ds_swizzle_b32 v98, v98 offset:swizzle(SWAP,16)
	s_waitcnt lgkmcnt(1)
	v_cndmask_b32_e64 v83, v97, v83, s[36:37]
	v_cndmask_b32_e64 v87, v87, v97, s[36:37]
	v_cndmask_b32_e64 v99, v85, v89, s[36:37]
	ds_swizzle_b32 v99, v99 offset:swizzle(SWAP,16)
	s_waitcnt lgkmcnt(1)
	v_cndmask_b32_e64 v84, v98, v84, s[36:37]
	v_cndmask_b32_e64 v88, v88, v98, s[36:37]
	s_waitcnt lgkmcnt(0)
	v_cndmask_b32_e64 v85, v99, v85, s[36:37]
	v_cndmask_b32_e64 v89, v89, v99, s[36:37]
	s_waitcnt vmcnt(11)
	v_lshl_add_u64 v[232:233], v[232:233], 0, s[78:79]
	global_load_dwordx4 v[188:191], v[232:233], off nt
	global_load_dwordx4 v[192:195], v[232:233], off offset:64 nt
	v_lshl_add_u64 v[232:233], v[232:233], 0, s[78:79]
	global_load_dwordx4 v[196:199], v[232:233], off nt
	global_load_dwordx4 v[200:203], v[232:233], off offset:64 nt
	v_lshlrev_b32_e32 v96, 16, v212
	v_and_b32_e32 v97, 0xffff0000, v212
	v_mul_f32_e32 v92, 0xbfb8aa3b, v96
	v_exp_f32_e32 v92, v92
	s_nop 0
	v_add_f32_e32 v92, 1.0, v92
	v_rcp_f32_e32 v98, v92
	v_mul_f32_e32 v92, 0xbfb8aa3b, v97
	v_exp_f32_e32 v92, v92
	s_nop 0
	v_add_f32_e32 v92, 1.0, v92
	v_rcp_f32_e32 v99, v92
	v_lshlrev_b32_e32 v92, 16, v213
	v_and_b32_e32 v93, 0xffff0000, v213
	v_pk_mul_f32 v[96:97], v[98:99], v[96:97]
	s_nop 0
	v_pk_mul_f32 v[82:83], v[96:97], v[82:83]
	ds_read2_b32 v[98:99], v162 offset0:64 offset1:80
	v_cvt_pk_bf16_f32 v82, v82, v83
	v_mul_f32_e32 v83, 0xbfb8aa3b, v92
	v_exp_f32_e32 v83, v83
	s_nop 0
	v_add_f32_e32 v83, 1.0, v83
	v_rcp_f32_e32 v96, v83
	v_mul_f32_e32 v83, 0xbfb8aa3b, v93
	v_exp_f32_e32 v83, v83
	s_nop 0
	v_add_f32_e32 v83, 1.0, v83
	v_rcp_f32_e32 v97, v83
	s_nop 0
	v_pk_mul_f32 v[92:93], v[96:97], v[92:93]
	s_nop 0
	v_pk_mul_f32 v[84:85], v[92:93], v[84:85]
	ds_read2_b32 v[96:97], v160 offset0:192 offset1:208
	v_cvt_pk_bf16_f32 v83, v84, v85
	v_lshlrev_b32_e32 v84, 16, v214
	v_and_b32_e32 v85, 0xffff0000, v214
	v_mul_f32_e32 v92, 0xbfb8aa3b, v84
	v_mul_f32_e32 v93, 0xbfb8aa3b, v85
	v_exp_f32_e32 v92, v92
	v_exp_f32_e32 v93, v93
	v_add_f32_e32 v92, 1.0, v92
	v_add_f32_e32 v93, 1.0, v93
	v_rcp_f32_e32 v92, v92
	v_rcp_f32_e32 v93, v93
	s_nop 0
	v_pk_mul_f32 v[84:85], v[92:93], v[84:85]
	s_nop 0
	v_pk_mul_f32 v[84:85], v[84:85], v[86:87]
	v_lshlrev_b32_e32 v86, 16, v215
	v_cvt_pk_bf16_f32 v84, v84, v85
	v_mul_f32_e32 v85, 0xbfb8aa3b, v86
	v_exp_f32_e32 v85, v85
	v_and_b32_e32 v87, 0xffff0000, v215
	ds_read2_b32 v[94:95], v160 offset0:64 offset1:80
	v_add_f32_e32 v85, 1.0, v85
	v_rcp_f32_e32 v92, v85
	v_mul_f32_e32 v85, 0xbfb8aa3b, v87
	v_exp_f32_e32 v85, v85
	s_nop 0
	v_add_f32_e32 v85, 1.0, v85
	v_rcp_f32_e32 v93, v85
	s_nop 0
	v_pk_mul_f32 v[86:87], v[92:93], v[86:87]
	s_nop 0
	v_pk_mul_f32 v[86:87], v[86:87], v[88:89]
	ds_read2_b32 v[88:89], v186 offset0:192 offset1:208
	v_cvt_pk_bf16_f32 v85, v86, v87
	ds_read2_b32 v[86:87], v186 offset0:64 offset1:80
	global_store_dwordx4 v[90:91], v[82:85], off offset:2112
	ds_read2_b32 v[90:91], v158 offset0:64 offset1:80
	ds_read2_b32 v[92:93], v158 offset0:192 offset1:208
	s_waitcnt lgkmcnt(2)
	v_add_f32_e32 v82, 0, v86
	v_add_f32_e32 v82, v82, v88
	s_waitcnt lgkmcnt(1)
	v_add_f32_e32 v82, v82, v90
	s_waitcnt lgkmcnt(0)
	v_add_f32_e32 v82, v82, v92
	v_add_f32_e32 v82, v82, v94
	v_add_f32_e32 v82, v82, v96
	v_add_f32_e32 v82, v82, v98
	v_add_f32_e32 v82, v82, v100
	v_fmamk_f32 v82, v82, 0x3b000000, v172
	v_cmp_gt_f32_e32 vcc, s4, v82
	v_mul_f32_e32 v83, 0x4f800000, v82
	s_nop 0
	v_cndmask_b32_e32 v82, v82, v83, vcc
	v_sqrt_f32_e32 v83, v82
	s_nop 0
	v_add_u32_e32 v84, -1, v83
	v_fma_f32 v85, -v84, v83, v82
	v_cmp_ge_f32_e64 s[0:1], 0, v85
	v_add_u32_e32 v85, 1, v83
	s_nop 0
	v_cndmask_b32_e64 v84, v83, v84, s[0:1]
	v_fma_f32 v83, -v85, v83, v82
	v_cmp_lt_f32_e64 s[0:1], 0, v83
	s_nop 1
	v_cndmask_b32_e64 v83, v84, v85, s[0:1]
	v_mul_f32_e32 v84, 0x37800000, v83
	v_cndmask_b32_e32 v83, v83, v84, vcc
	v_cmp_class_f32_e32 vcc, v82, v173
	s_nop 1
	v_cndmask_b32_e32 v82, v83, v82, vcc
	v_div_scale_f32 v83, s[0:1], v82, v82, 1.0
	v_rcp_f32_e32 v84, v83
	s_nop 0
	v_fma_f32 v85, -v83, v84, 1.0
	v_fmac_f32_e32 v84, v85, v84
	v_div_scale_f32 v85, vcc, 1.0, v82, 1.0
	v_mul_f32_e32 v86, v85, v84
	v_fma_f32 v88, -v83, v86, v85
	v_fmac_f32_e32 v86, v88, v84
	v_fma_f32 v83, -v83, v86, v85
	v_div_fmas_f32 v83, v83, v84, v86
	v_div_fixup_f32 v86, v83, v82, 1.0
	v_or_b32_e32 v82, 64, v150
	v_ashrrev_i32_e32 v83, 31, v82
	v_lshlrev_b64 v[84:85], 9, v[82:83]
	v_lshl_add_u64 v[84:85], s[38:39], 0, v[84:85]
	v_mad_i64_i32 v[82:83], s[0:1], v82, s2, v[152:153]
	v_lshl_add_u64 v[104:105], v[84:85], 0, v[154:155]
	v_lshl_add_u64 v[102:103], v[82:83], 0, s[18:19]
	v_pk_mul_f32 v[76:77], v[76:77], v[86:87] op_sel_hi:[1,0]
	v_pk_mul_f32 v[80:81], v[80:81], v[86:87] op_sel_hi:[1,0]
	v_pk_mul_f32 v[76:77], v[32:33], v[76:77]
	v_pk_mul_f32 v[80:81], v[28:29], v[80:81]
	v_pk_mul_f32 v[74:75], v[74:75], v[86:87] op_sel_hi:[1,0]
	v_cndmask_b32_e64 v92, v76, v80, s[36:37]
	ds_swizzle_b32 v92, v92 offset:swizzle(SWAP,16)
	v_cndmask_b32_e64 v94, v77, v81, s[36:37]
	ds_swizzle_b32 v94, v94 offset:swizzle(SWAP,16)
	v_pk_mul_f32 v[78:79], v[78:79], v[86:87] op_sel_hi:[1,0]
	v_pk_mul_f32 v[74:75], v[30:31], v[74:75]
	s_waitcnt lgkmcnt(1)
	v_cndmask_b32_e64 v106, v92, v76, s[36:37]
	v_pk_mul_f32 v[78:79], v[26:27], v[78:79]
	s_waitcnt lgkmcnt(0)
	v_cndmask_b32_e64 v107, v94, v77, s[36:37]
	v_cndmask_b32_e64 v88, v74, v78, s[36:37]
	v_cndmask_b32_e64 v90, v75, v79, s[36:37]
	ds_swizzle_b32 v88, v88 offset:swizzle(SWAP,16)
	ds_swizzle_b32 v90, v90 offset:swizzle(SWAP,16)
	v_cndmask_b32_e64 v81, v81, v94, s[36:37]
	v_cndmask_b32_e64 v80, v80, v92, s[36:37]
	v_pk_mul_f32 v[70:71], v[70:71], v[86:87] op_sel_hi:[1,0]
	s_waitcnt lgkmcnt(1)
	v_cndmask_b32_e64 v74, v88, v74, s[36:37]
	s_waitcnt lgkmcnt(0)
	v_cndmask_b32_e64 v75, v90, v75, s[36:37]
	v_cndmask_b32_e64 v79, v79, v90, s[36:37]
	v_cndmask_b32_e64 v78, v78, v88, s[36:37]
	v_pk_mul_f32 v[66:67], v[66:67], v[86:87] op_sel_hi:[1,0]
	v_pk_mul_f32 v[70:71], v[22:23], v[70:71]
	v_pk_mul_f32 v[66:67], v[18:19], v[66:67]
	v_pk_mul_f32 v[72:73], v[72:73], v[86:87] op_sel_hi:[1,0]
	v_pk_mul_f32 v[68:69], v[68:69], v[86:87] op_sel_hi:[1,0]
	v_pk_mul_f32 v[72:73], v[24:25], v[72:73]
	v_pk_mul_f32 v[68:69], v[20:21], v[68:69]
	s_waitcnt vmcnt(15)
	v_lshlrev_b32_e32 v76, 16, v216
	v_and_b32_e32 v77, 0xffff0000, v216
	v_mul_f32_e32 v82, 0xbfb8aa3b, v76
	v_exp_f32_e32 v82, v82
	s_nop 0
	v_add_f32_e32 v82, 1.0, v82
	v_rcp_f32_e32 v108, v82
	v_mul_f32_e32 v82, 0xbfb8aa3b, v77
	v_exp_f32_e32 v82, v82
	s_nop 0
	v_add_f32_e32 v82, 1.0, v82
	v_rcp_f32_e32 v109, v82
	s_nop 0
	v_pk_mul_f32 v[76:77], v[108:109], v[76:77]
	s_nop 0
	v_pk_mul_f32 v[74:75], v[76:77], v[74:75]
	s_nop 0
	v_cvt_pk_bf16_f32 v76, v74, v75
	v_lshlrev_b32_e32 v74, 16, v217
	v_mul_f32_e32 v77, 0xbfb8aa3b, v74
	v_exp_f32_e32 v77, v77
	v_and_b32_e32 v75, 0xffff0000, v217
	v_add_f32_e32 v77, 1.0, v77
	v_rcp_f32_e32 v82, v77
	v_mul_f32_e32 v77, 0xbfb8aa3b, v75
	v_exp_f32_e32 v77, v77
	s_nop 0
	v_add_f32_e32 v77, 1.0, v77
	v_rcp_f32_e32 v83, v77
	s_nop 0
	v_pk_mul_f32 v[74:75], v[82:83], v[74:75]
	s_nop 0
	v_pk_mul_f32 v[74:75], v[74:75], v[106:107]
	s_nop 0
	v_cvt_pk_bf16_f32 v77, v74, v75
	v_lshlrev_b32_e32 v74, 16, v218
	v_and_b32_e32 v75, 0xffff0000, v218
	v_mul_f32_e32 v82, 0xbfb8aa3b, v74
	v_mul_f32_e32 v83, 0xbfb8aa3b, v75
	v_exp_f32_e32 v82, v82
	v_exp_f32_e32 v83, v83
	v_add_f32_e32 v82, 1.0, v82
	v_add_f32_e32 v83, 1.0, v83
	v_rcp_f32_e32 v82, v82
	v_rcp_f32_e32 v83, v83
	s_nop 0
	v_pk_mul_f32 v[74:75], v[82:83], v[74:75]
	s_nop 0
	v_pk_mul_f32 v[74:75], v[74:75], v[78:79]
	s_nop 0
	v_cvt_pk_bf16_f32 v78, v74, v75
	v_lshlrev_b32_e32 v74, 16, v219
	v_mul_f32_e32 v79, 0xbfb8aa3b, v74
	v_exp_f32_e32 v79, v79
	v_and_b32_e32 v75, 0xffff0000, v219
	v_add_f32_e32 v79, 1.0, v79
	v_rcp_f32_e32 v82, v79
	v_mul_f32_e32 v79, 0xbfb8aa3b, v75
	v_exp_f32_e32 v79, v79
	s_nop 0
	v_add_f32_e32 v79, 1.0, v79
	v_rcp_f32_e32 v83, v79
	s_nop 0
	v_pk_mul_f32 v[74:75], v[82:83], v[74:75]
	s_nop 0
	v_pk_mul_f32 v[74:75], v[74:75], v[80:81]
	v_cndmask_b32_e64 v80, v70, v66, s[36:37]
	v_cvt_pk_bf16_f32 v79, v74, v75
	v_lshl_add_u64 v[74:75], v[102:103], 0, v[138:139]
	global_store_dwordx4 v[74:75], v[76:79], off offset:2048
	ds_swizzle_b32 v82, v80 offset:swizzle(SWAP,16)
	v_cndmask_b32_e64 v80, v71, v67, s[36:37]
	ds_swizzle_b32 v83, v80 offset:swizzle(SWAP,16)
	v_cndmask_b32_e64 v80, v72, v68, s[36:37]
	ds_swizzle_b32 v80, v80 offset:swizzle(SWAP,16)
	v_cndmask_b32_e64 v81, v73, v69, s[36:37]
	ds_swizzle_b32 v81, v81 offset:swizzle(SWAP,16)
	s_waitcnt lgkmcnt(3)
	v_cndmask_b32_e64 v70, v82, v70, s[36:37]
	s_waitcnt lgkmcnt(2)
	v_cndmask_b32_e64 v71, v83, v71, s[36:37]
	s_waitcnt lgkmcnt(1)
	v_cndmask_b32_e64 v72, v80, v72, s[36:37]
	v_cndmask_b32_e64 v80, v68, v80, s[36:37]
	v_cndmask_b32_e64 v68, v66, v82, s[36:37]
	s_waitcnt lgkmcnt(0)
	v_cndmask_b32_e64 v73, v81, v73, s[36:37]
	v_cndmask_b32_e64 v81, v69, v81, s[36:37]
	v_cndmask_b32_e64 v69, v67, v83, s[36:37]
	s_waitcnt vmcnt(15)
	v_lshlrev_b32_e32 v66, 16, v220
	v_and_b32_e32 v67, 0xffff0000, v220
	v_mul_f32_e32 v76, 0xbfb8aa3b, v66
	v_exp_f32_e32 v76, v76
	s_nop 0
	v_add_f32_e32 v76, 1.0, v76
	v_rcp_f32_e32 v82, v76
	v_mul_f32_e32 v76, 0xbfb8aa3b, v67
	v_exp_f32_e32 v76, v76
	s_nop 0
	v_add_f32_e32 v76, 1.0, v76
	v_rcp_f32_e32 v83, v76
	s_nop 0
	v_pk_mul_f32 v[66:67], v[82:83], v[66:67]
	s_nop 0
	v_pk_mul_f32 v[66:67], v[66:67], v[70:71]
	v_lshlrev_b32_e32 v70, 16, v221
	v_cvt_pk_bf16_f32 v66, v66, v67
	v_mul_f32_e32 v67, 0xbfb8aa3b, v70
	v_exp_f32_e32 v67, v67
	v_and_b32_e32 v71, 0xffff0000, v221
	v_add_f32_e32 v67, 1.0, v67
	v_rcp_f32_e32 v76, v67
	v_mul_f32_e32 v67, 0xbfb8aa3b, v71
	v_exp_f32_e32 v67, v67
	s_nop 0
	v_add_f32_e32 v67, 1.0, v67
	v_rcp_f32_e32 v77, v67
	s_nop 0
	v_pk_mul_f32 v[70:71], v[76:77], v[70:71]
	s_nop 0
	v_pk_mul_f32 v[70:71], v[70:71], v[72:73]
	s_nop 0
	v_cvt_pk_bf16_f32 v67, v70, v71
	v_lshlrev_b32_e32 v70, 16, v222
	v_and_b32_e32 v71, 0xffff0000, v222
	v_mul_f32_e32 v72, 0xbfb8aa3b, v70
	v_mul_f32_e32 v73, 0xbfb8aa3b, v71
	v_exp_f32_e32 v72, v72
	v_exp_f32_e32 v73, v73
	v_add_f32_e32 v72, 1.0, v72
	v_add_f32_e32 v73, 1.0, v73
	v_rcp_f32_e32 v72, v72
	v_rcp_f32_e32 v73, v73
	s_nop 0
	v_pk_mul_f32 v[70:71], v[72:73], v[70:71]
	s_nop 0
	v_pk_mul_f32 v[68:69], v[70:71], v[68:69]
	v_lshlrev_b32_e32 v70, 16, v223
	v_cvt_pk_bf16_f32 v68, v68, v69
	v_mul_f32_e32 v69, 0xbfb8aa3b, v70
	v_exp_f32_e32 v69, v69
	v_and_b32_e32 v71, 0xffff0000, v223
	v_add_f32_e32 v69, 1.0, v69
	v_rcp_f32_e32 v72, v69
	v_mul_f32_e32 v69, 0xbfb8aa3b, v71
	v_exp_f32_e32 v69, v69
	s_nop 0
	v_add_f32_e32 v69, 1.0, v69
	v_rcp_f32_e32 v73, v69
	s_nop 0
	v_pk_mul_f32 v[70:71], v[72:73], v[70:71]
	s_nop 0
	v_pk_mul_f32 v[70:71], v[70:71], v[80:81]
	s_nop 0
	v_cvt_pk_bf16_f32 v69, v70, v71
	global_store_dwordx4 v[74:75], v[66:69], off offset:2112
	s_nop 1
	v_add_f32_e32 v66, 0, v87
	v_add_f32_e32 v66, v66, v89
	v_add_f32_e32 v66, v66, v91
	v_add_f32_e32 v66, v66, v93
	v_add_f32_e32 v66, v66, v95
	v_add_f32_e32 v66, v66, v97
	v_add_f32_e32 v66, v66, v99
	v_add_f32_e32 v66, v66, v101
	v_fmamk_f32 v66, v66, 0x3b000000, v172
	v_cmp_gt_f32_e32 vcc, s4, v66
	v_mul_f32_e32 v67, 0x4f800000, v66
	s_nop 0
	v_cndmask_b32_e32 v66, v66, v67, vcc
	v_sqrt_f32_e32 v67, v66
	s_nop 0
	v_add_u32_e32 v68, -1, v67
	v_fma_f32 v69, -v68, v67, v66
	v_cmp_ge_f32_e64 s[0:1], 0, v69
	v_add_u32_e32 v69, 1, v67
	s_nop 0
	v_cndmask_b32_e64 v68, v67, v68, s[0:1]
	v_fma_f32 v67, -v69, v67, v66
	v_cmp_lt_f32_e64 s[0:1], 0, v67
	s_nop 1
	v_cndmask_b32_e64 v67, v68, v69, s[0:1]
	v_mul_f32_e32 v68, 0x37800000, v67
	v_cndmask_b32_e32 v67, v67, v68, vcc
	v_cmp_class_f32_e32 vcc, v66, v173
	s_nop 1
	v_cndmask_b32_e32 v66, v67, v66, vcc
	v_div_scale_f32 v67, s[0:1], v66, v66, 1.0
	v_rcp_f32_e32 v68, v67
	s_nop 0
	v_fma_f32 v69, -v67, v68, 1.0
	v_fmac_f32_e32 v68, v69, v68
	v_div_scale_f32 v69, vcc, 1.0, v66, 1.0
	v_mul_f32_e32 v70, v69, v68
	v_fma_f32 v71, -v67, v70, v69
	v_fmac_f32_e32 v70, v71, v68
	v_fma_f32 v67, -v67, v70, v69
	v_div_fmas_f32 v67, v67, v68, v70
	v_div_fixup_f32 v70, v67, v66, 1.0
	v_or_b32_e32 v66, 0x50, v150
	v_ashrrev_i32_e32 v67, 31, v66
	v_lshlrev_b64 v[68:69], 9, v[66:67]
	v_lshl_add_u64 v[68:69], s[38:39], 0, v[68:69]
	v_mad_i64_i32 v[66:67], s[0:1], v66, s2, v[152:153]
	v_lshl_add_u64 v[74:75], v[68:69], 0, v[154:155]
	v_lshl_add_u64 v[72:73], v[66:67], 0, s[18:19]
	v_pk_mul_f32 v[58:59], v[58:59], v[70:71] op_sel_hi:[1,0]
	v_pk_mul_f32 v[62:63], v[62:63], v[70:71] op_sel_hi:[1,0]
	v_pk_mul_f32 v[60:61], v[60:61], v[70:71] op_sel_hi:[1,0]
	v_pk_mul_f32 v[58:59], v[30:31], v[58:59]
	v_pk_mul_f32 v[64:65], v[64:65], v[70:71] op_sel_hi:[1,0]
	v_pk_mul_f32 v[62:63], v[26:27], v[62:63]
	v_pk_mul_f32 v[60:61], v[32:33], v[60:61]
	v_pk_mul_f32 v[64:65], v[28:29], v[64:65]
	v_cndmask_b32_e64 v76, v59, v63, s[36:37]
	ds_swizzle_b32 v78, v76 offset:swizzle(SWAP,16)
	v_cndmask_b32_e64 v76, v60, v64, s[36:37]
	ds_swizzle_b32 v79, v76 offset:swizzle(SWAP,16)
	v_cndmask_b32_e64 v76, v61, v65, s[36:37]
	ds_swizzle_b32 v80, v76 offset:swizzle(SWAP,16)
	s_waitcnt lgkmcnt(2)
	v_cndmask_b32_e64 v59, v78, v59, s[36:37]
	v_cndmask_b32_e64 v63, v63, v78, s[36:37]
	s_waitcnt lgkmcnt(1)
	v_cndmask_b32_e64 v76, v79, v60, s[36:37]
	v_cndmask_b32_e64 v71, v58, v62, s[36:37]
	s_waitcnt lgkmcnt(0)
	v_cndmask_b32_e64 v77, v80, v61, s[36:37]
	ds_swizzle_b32 v71, v71 offset:swizzle(SWAP,16)
	v_cndmask_b32_e64 v64, v64, v79, s[36:37]
	v_cndmask_b32_e64 v65, v65, v80, s[36:37]
	s_waitcnt lgkmcnt(0)
	v_cndmask_b32_e64 v58, v71, v58, s[36:37]
	v_cndmask_b32_e64 v62, v62, v71, s[36:37]
	v_pk_mul_f32 v[54:55], v[54:55], v[70:71] op_sel_hi:[1,0]
	v_pk_mul_f32 v[50:51], v[50:51], v[70:71] op_sel_hi:[1,0]
	v_pk_mul_f32 v[54:55], v[22:23], v[54:55]
	v_pk_mul_f32 v[50:51], v[18:19], v[50:51]
	v_pk_mul_f32 v[56:57], v[56:57], v[70:71] op_sel_hi:[1,0]
	v_pk_mul_f32 v[52:53], v[52:53], v[70:71] op_sel_hi:[1,0]
	v_pk_mul_f32 v[56:57], v[24:25], v[56:57]
	v_pk_mul_f32 v[52:53], v[20:21], v[52:53]
	s_waitcnt vmcnt(15)
	v_lshlrev_b32_e32 v60, 16, v224
	v_and_b32_e32 v61, 0xffff0000, v224
	v_mul_f32_e32 v66, 0xbfb8aa3b, v60
	v_exp_f32_e32 v66, v66
	s_nop 0
	v_add_f32_e32 v66, 1.0, v66
	v_rcp_f32_e32 v78, v66
	v_mul_f32_e32 v66, 0xbfb8aa3b, v61
	v_exp_f32_e32 v66, v66
	s_nop 0
	v_add_f32_e32 v66, 1.0, v66
	v_rcp_f32_e32 v79, v66
	s_nop 0
	v_pk_mul_f32 v[60:61], v[78:79], v[60:61]
	s_nop 0
	v_pk_mul_f32 v[58:59], v[60:61], v[58:59]
	s_nop 0
	v_cvt_pk_bf16_f32 v60, v58, v59
	v_lshlrev_b32_e32 v58, 16, v225
	v_mul_f32_e32 v61, 0xbfb8aa3b, v58
	v_exp_f32_e32 v61, v61
	v_and_b32_e32 v59, 0xffff0000, v225
	v_add_f32_e32 v61, 1.0, v61
	v_rcp_f32_e32 v66, v61
	v_mul_f32_e32 v61, 0xbfb8aa3b, v59
	v_exp_f32_e32 v61, v61
	s_nop 0
	v_add_f32_e32 v61, 1.0, v61
	v_rcp_f32_e32 v67, v61
	s_nop 0
	v_pk_mul_f32 v[58:59], v[66:67], v[58:59]
	s_nop 0
	v_pk_mul_f32 v[58:59], v[58:59], v[76:77]
	s_nop 0
	v_cvt_pk_bf16_f32 v61, v58, v59
	v_lshlrev_b32_e32 v58, 16, v226
	v_and_b32_e32 v59, 0xffff0000, v226
	v_mul_f32_e32 v66, 0xbfb8aa3b, v58
	v_mul_f32_e32 v67, 0xbfb8aa3b, v59
	v_exp_f32_e32 v66, v66
	v_exp_f32_e32 v67, v67
	v_add_f32_e32 v66, 1.0, v66
	v_add_f32_e32 v67, 1.0, v67
	v_rcp_f32_e32 v66, v66
	v_rcp_f32_e32 v67, v67
	s_nop 0
	v_pk_mul_f32 v[58:59], v[66:67], v[58:59]
	s_nop 0
	v_pk_mul_f32 v[58:59], v[58:59], v[62:63]
	s_nop 0
	v_cvt_pk_bf16_f32 v62, v58, v59
	v_lshlrev_b32_e32 v58, 16, v227
	v_mul_f32_e32 v63, 0xbfb8aa3b, v58
	v_exp_f32_e32 v63, v63
	v_and_b32_e32 v59, 0xffff0000, v227
	ds_read2_b32 v[68:69], v162 offset0:224 offset1:240
	v_add_f32_e32 v63, 1.0, v63
	v_rcp_f32_e32 v66, v63
	v_mul_f32_e32 v63, 0xbfb8aa3b, v59
	v_exp_f32_e32 v63, v63
	s_nop 0
	v_add_f32_e32 v63, 1.0, v63
	v_rcp_f32_e32 v67, v63
	s_nop 0
	v_pk_mul_f32 v[58:59], v[66:67], v[58:59]
	s_nop 0
	v_pk_mul_f32 v[58:59], v[58:59], v[64:65]
	v_cndmask_b32_e64 v64, v54, v50, s[36:37]
	v_cvt_pk_bf16_f32 v63, v58, v59
	v_lshl_add_u64 v[58:59], v[72:73], 0, v[138:139]
	global_store_dwordx4 v[58:59], v[60:63], off offset:2048
	ds_swizzle_b32 v66, v64 offset:swizzle(SWAP,16)
	v_cndmask_b32_e64 v64, v55, v51, s[36:37]
	ds_swizzle_b32 v67, v64 offset:swizzle(SWAP,16)
	v_cndmask_b32_e64 v64, v56, v52, s[36:37]
	ds_swizzle_b32 v64, v64 offset:swizzle(SWAP,16)
	v_cndmask_b32_e64 v65, v57, v53, s[36:37]
	ds_swizzle_b32 v65, v65 offset:swizzle(SWAP,16)
	s_waitcnt lgkmcnt(3)
	v_cndmask_b32_e64 v54, v66, v54, s[36:37]
	s_waitcnt lgkmcnt(2)
	v_cndmask_b32_e64 v55, v67, v55, s[36:37]
	s_waitcnt lgkmcnt(1)
	v_cndmask_b32_e64 v56, v64, v56, s[36:37]
	v_cndmask_b32_e64 v64, v52, v64, s[36:37]
	v_cndmask_b32_e64 v52, v50, v66, s[36:37]
	s_waitcnt lgkmcnt(0)
	v_cndmask_b32_e64 v57, v65, v57, s[36:37]
	v_cndmask_b32_e64 v65, v53, v65, s[36:37]
	v_cndmask_b32_e64 v53, v51, v67, s[36:37]
	s_waitcnt vmcnt(15)
	v_lshlrev_b32_e32 v50, 16, v228
	v_and_b32_e32 v51, 0xffff0000, v228
	v_mul_f32_e32 v60, 0xbfb8aa3b, v50
	v_exp_f32_e32 v60, v60
	s_nop 0
	v_add_f32_e32 v60, 1.0, v60
	v_rcp_f32_e32 v66, v60
	v_mul_f32_e32 v60, 0xbfb8aa3b, v51
	v_exp_f32_e32 v60, v60
	s_nop 0
	v_add_f32_e32 v60, 1.0, v60
	v_rcp_f32_e32 v67, v60
	s_nop 0
	v_pk_mul_f32 v[50:51], v[66:67], v[50:51]
	s_nop 0
	v_pk_mul_f32 v[50:51], v[50:51], v[54:55]
	v_lshlrev_b32_e32 v54, 16, v229
	v_cvt_pk_bf16_f32 v50, v50, v51
	v_mul_f32_e32 v51, 0xbfb8aa3b, v54
	v_exp_f32_e32 v51, v51
	v_and_b32_e32 v55, 0xffff0000, v229
	ds_read2_b32 v[66:67], v162 offset0:96 offset1:112
	v_add_f32_e32 v51, 1.0, v51
	v_rcp_f32_e32 v60, v51
	v_mul_f32_e32 v51, 0xbfb8aa3b, v55
	v_exp_f32_e32 v51, v51
	s_nop 0
	v_add_f32_e32 v51, 1.0, v51
	v_rcp_f32_e32 v61, v51
	s_nop 0
	v_pk_mul_f32 v[54:55], v[60:61], v[54:55]
	s_nop 0
	v_pk_mul_f32 v[54:55], v[54:55], v[56:57]
	ds_read2_b32 v[60:61], v158 offset0:224 offset1:240
	v_cvt_pk_bf16_f32 v51, v54, v55
	v_lshlrev_b32_e32 v54, 16, v230
	v_and_b32_e32 v55, 0xffff0000, v230
	v_mul_f32_e32 v56, 0xbfb8aa3b, v54
	v_mul_f32_e32 v57, 0xbfb8aa3b, v55
	v_exp_f32_e32 v56, v56
	v_exp_f32_e32 v57, v57
	v_add_f32_e32 v56, 1.0, v56
	v_add_f32_e32 v57, 1.0, v57
	v_rcp_f32_e32 v56, v56
	v_rcp_f32_e32 v57, v57
	s_nop 0
	v_pk_mul_f32 v[54:55], v[56:57], v[54:55]
	s_nop 0
	v_pk_mul_f32 v[52:53], v[54:55], v[52:53]
	v_lshlrev_b32_e32 v54, 16, v231
	v_cvt_pk_bf16_f32 v52, v52, v53
	v_mul_f32_e32 v53, 0xbfb8aa3b, v54
	v_exp_f32_e32 v53, v53
	v_and_b32_e32 v55, 0xffff0000, v231
	ds_read2_b32 v[62:63], v160 offset0:96 offset1:112
	v_add_f32_e32 v53, 1.0, v53
	v_rcp_f32_e32 v56, v53
	v_mul_f32_e32 v53, 0xbfb8aa3b, v55
	v_exp_f32_e32 v53, v53
	s_nop 0
	v_add_f32_e32 v53, 1.0, v53
	v_rcp_f32_e32 v57, v53
	s_nop 0
	v_pk_mul_f32 v[54:55], v[56:57], v[54:55]
	s_nop 0
	v_pk_mul_f32 v[54:55], v[54:55], v[64:65]
	ds_read2_b32 v[56:57], v186 offset0:224 offset1:240
	v_cvt_pk_bf16_f32 v53, v54, v55
	ds_read2_b32 v[54:55], v186 offset0:96 offset1:112
	global_store_dwordx4 v[58:59], v[50:53], off offset:2112
	ds_read2_b32 v[58:59], v158 offset0:96 offset1:112
	ds_read2_b32 v[64:65], v160 offset0:224 offset1:240
	s_waitcnt lgkmcnt(2)
	v_add_f32_e32 v50, 0, v54
	v_add_f32_e32 v50, v50, v56
	s_waitcnt lgkmcnt(1)
	v_add_f32_e32 v50, v50, v58
	v_add_f32_e32 v50, v50, v60
	v_add_f32_e32 v50, v50, v62
	s_waitcnt lgkmcnt(0)
	v_add_f32_e32 v50, v50, v64
	v_add_f32_e32 v50, v50, v66
	v_add_f32_e32 v50, v50, v68
	v_fmamk_f32 v50, v50, 0x3b000000, v172
	v_cmp_gt_f32_e32 vcc, s4, v50
	v_mul_f32_e32 v51, 0x4f800000, v50
	s_nop 0
	v_cndmask_b32_e32 v50, v50, v51, vcc
	v_sqrt_f32_e32 v51, v50
	s_nop 0
	v_add_u32_e32 v52, -1, v51
	v_fma_f32 v53, -v52, v51, v50
	v_cmp_ge_f32_e64 s[0:1], 0, v53
	v_add_u32_e32 v53, 1, v51
	s_nop 0
	v_cndmask_b32_e64 v52, v51, v52, s[0:1]
	v_fma_f32 v51, -v53, v51, v50
	v_cmp_lt_f32_e64 s[0:1], 0, v51
	s_nop 1
	v_cndmask_b32_e64 v51, v52, v53, s[0:1]
	v_mul_f32_e32 v52, 0x37800000, v51
	v_cndmask_b32_e32 v51, v51, v52, vcc
	v_cmp_class_f32_e32 vcc, v50, v173
	s_nop 1
	v_cndmask_b32_e32 v50, v51, v50, vcc
	v_div_scale_f32 v51, s[0:1], v50, v50, 1.0
	v_rcp_f32_e32 v52, v51
	s_nop 0
	v_fma_f32 v53, -v51, v52, 1.0
	v_fmac_f32_e32 v52, v53, v52
	v_div_scale_f32 v53, vcc, 1.0, v50, 1.0
	v_mul_f32_e32 v54, v53, v52
	v_fma_f32 v56, -v51, v54, v53
	v_fmac_f32_e32 v54, v56, v52
	v_fma_f32 v51, -v51, v54, v53
	v_div_fmas_f32 v51, v51, v52, v54
	v_div_fixup_f32 v54, v51, v50, 1.0
	v_or_b32_e32 v50, 0x60, v150
	v_ashrrev_i32_e32 v51, 31, v50
	v_lshlrev_b64 v[52:53], 9, v[50:51]
	v_lshl_add_u64 v[52:53], s[38:39], 0, v[52:53]
	v_mad_i64_i32 v[50:51], s[0:1], v50, s2, v[152:153]
	v_lshl_add_u64 v[72:73], v[52:53], 0, v[154:155]
	v_lshl_add_u64 v[70:71], v[50:51], 0, s[18:19]
	v_pk_mul_f32 v[48:49], v[48:49], v[54:55] op_sel_hi:[1,0]
	v_pk_mul_f32 v[44:45], v[44:45], v[54:55] op_sel_hi:[1,0]
	v_pk_mul_f32 v[48:49], v[32:33], v[48:49]
	v_pk_mul_f32 v[44:45], v[28:29], v[44:45]
	v_pk_mul_f32 v[46:47], v[46:47], v[54:55] op_sel_hi:[1,0]
	v_cndmask_b32_e64 v60, v48, v44, s[36:37]
	ds_swizzle_b32 v60, v60 offset:swizzle(SWAP,16)
	v_cndmask_b32_e64 v62, v49, v45, s[36:37]
	ds_swizzle_b32 v62, v62 offset:swizzle(SWAP,16)
	v_pk_mul_f32 v[42:43], v[42:43], v[54:55] op_sel_hi:[1,0]
	v_pk_mul_f32 v[46:47], v[30:31], v[46:47]
	s_waitcnt lgkmcnt(1)
	v_cndmask_b32_e64 v74, v44, v60, s[36:37]
	v_pk_mul_f32 v[42:43], v[26:27], v[42:43]
	s_waitcnt lgkmcnt(0)
	v_cndmask_b32_e64 v75, v45, v62, s[36:37]
	v_cndmask_b32_e64 v56, v46, v42, s[36:37]
	v_cndmask_b32_e64 v58, v47, v43, s[36:37]
	ds_swizzle_b32 v56, v56 offset:swizzle(SWAP,16)
	ds_swizzle_b32 v58, v58 offset:swizzle(SWAP,16)
	v_cndmask_b32_e64 v49, v62, v49, s[36:37]
	v_cndmask_b32_e64 v48, v60, v48, s[36:37]
	v_pk_mul_f32 v[38:39], v[38:39], v[54:55] op_sel_hi:[1,0]
	s_waitcnt lgkmcnt(1)
	v_cndmask_b32_e64 v46, v56, v46, s[36:37]
	s_waitcnt lgkmcnt(0)
	v_cndmask_b32_e64 v47, v58, v47, s[36:37]
	v_cndmask_b32_e64 v43, v43, v58, s[36:37]
	v_cndmask_b32_e64 v42, v42, v56, s[36:37]
	v_pk_mul_f32 v[34:35], v[34:35], v[54:55] op_sel_hi:[1,0]
	v_pk_mul_f32 v[38:39], v[22:23], v[38:39]
	v_pk_mul_f32 v[34:35], v[18:19], v[34:35]
	v_pk_mul_f32 v[40:41], v[40:41], v[54:55] op_sel_hi:[1,0]
	v_pk_mul_f32 v[36:37], v[36:37], v[54:55] op_sel_hi:[1,0]
	v_pk_mul_f32 v[40:41], v[24:25], v[40:41]
	v_pk_mul_f32 v[36:37], v[20:21], v[36:37]
	s_waitcnt vmcnt(8)
	v_lshlrev_b32_e32 v44, 16, v188
	v_and_b32_e32 v45, 0xffff0000, v188
	v_mul_f32_e32 v50, 0xbfb8aa3b, v44
	v_exp_f32_e32 v50, v50
	s_nop 0
	v_add_f32_e32 v50, 1.0, v50
	v_rcp_f32_e32 v76, v50
	v_mul_f32_e32 v50, 0xbfb8aa3b, v45
	v_exp_f32_e32 v50, v50
	s_nop 0
	v_add_f32_e32 v50, 1.0, v50
	v_rcp_f32_e32 v77, v50
	s_nop 0
	v_pk_mul_f32 v[44:45], v[76:77], v[44:45]
	s_nop 0
	v_pk_mul_f32 v[44:45], v[44:45], v[46:47]
	v_lshlrev_b32_e32 v46, 16, v189
	v_cvt_pk_bf16_f32 v44, v44, v45
	v_mul_f32_e32 v45, 0xbfb8aa3b, v46
	v_exp_f32_e32 v45, v45
	v_and_b32_e32 v47, 0xffff0000, v189
	v_add_f32_e32 v45, 1.0, v45
	v_rcp_f32_e32 v50, v45
	v_mul_f32_e32 v45, 0xbfb8aa3b, v47
	v_exp_f32_e32 v45, v45
	s_nop 0
	v_add_f32_e32 v45, 1.0, v45
	v_rcp_f32_e32 v51, v45
	s_nop 0
	v_pk_mul_f32 v[46:47], v[50:51], v[46:47]
	s_nop 0
	v_pk_mul_f32 v[46:47], v[46:47], v[48:49]
	s_nop 0
	v_cvt_pk_bf16_f32 v45, v46, v47
	v_lshlrev_b32_e32 v46, 16, v190
	v_and_b32_e32 v47, 0xffff0000, v190
	v_mul_f32_e32 v48, 0xbfb8aa3b, v46
	v_mul_f32_e32 v49, 0xbfb8aa3b, v47
	v_exp_f32_e32 v48, v48
	v_exp_f32_e32 v49, v49
	v_add_f32_e32 v48, 1.0, v48
	v_add_f32_e32 v49, 1.0, v49
	v_rcp_f32_e32 v48, v48
	v_rcp_f32_e32 v49, v49
	s_nop 0
	v_pk_mul_f32 v[46:47], v[48:49], v[46:47]
	s_nop 0
	v_pk_mul_f32 v[42:43], v[46:47], v[42:43]
	s_nop 0
	v_cvt_pk_bf16_f32 v46, v42, v43
	v_lshlrev_b32_e32 v42, 16, v191
	v_mul_f32_e32 v47, 0xbfb8aa3b, v42
	v_exp_f32_e32 v47, v47
	v_and_b32_e32 v43, 0xffff0000, v191
	v_add_f32_e32 v47, 1.0, v47
	v_rcp_f32_e32 v48, v47
	v_mul_f32_e32 v47, 0xbfb8aa3b, v43
	v_exp_f32_e32 v47, v47
	s_nop 0
	v_add_f32_e32 v47, 1.0, v47
	v_rcp_f32_e32 v49, v47
	s_nop 0
	v_pk_mul_f32 v[42:43], v[48:49], v[42:43]
	s_nop 0
	v_pk_mul_f32 v[42:43], v[42:43], v[74:75]
	v_cndmask_b32_e64 v48, v38, v34, s[36:37]
	v_cvt_pk_bf16_f32 v47, v42, v43
	v_lshl_add_u64 v[42:43], v[70:71], 0, v[138:139]
	global_store_dwordx4 v[42:43], v[44:47], off offset:2048
	ds_swizzle_b32 v50, v48 offset:swizzle(SWAP,16)
	v_cndmask_b32_e64 v48, v39, v35, s[36:37]
	ds_swizzle_b32 v51, v48 offset:swizzle(SWAP,16)
	v_cndmask_b32_e64 v48, v40, v36, s[36:37]
	ds_swizzle_b32 v48, v48 offset:swizzle(SWAP,16)
	v_cndmask_b32_e64 v49, v41, v37, s[36:37]
	ds_swizzle_b32 v49, v49 offset:swizzle(SWAP,16)
	s_waitcnt lgkmcnt(3)
	v_cndmask_b32_e64 v38, v50, v38, s[36:37]
	s_waitcnt lgkmcnt(2)
	v_cndmask_b32_e64 v39, v51, v39, s[36:37]
	s_waitcnt lgkmcnt(1)
	v_cndmask_b32_e64 v40, v48, v40, s[36:37]
	v_cndmask_b32_e64 v48, v36, v48, s[36:37]
	v_cndmask_b32_e64 v36, v34, v50, s[36:37]
	s_waitcnt lgkmcnt(0)
	v_cndmask_b32_e64 v41, v49, v41, s[36:37]
	v_cndmask_b32_e64 v49, v37, v49, s[36:37]
	v_cndmask_b32_e64 v37, v35, v51, s[36:37]
	s_waitcnt vmcnt(8)
	v_lshlrev_b32_e32 v34, 16, v192
	v_and_b32_e32 v35, 0xffff0000, v192
	v_mul_f32_e32 v44, 0xbfb8aa3b, v34
	v_exp_f32_e32 v44, v44
	s_nop 0
	v_add_f32_e32 v44, 1.0, v44
	v_rcp_f32_e32 v50, v44
	v_mul_f32_e32 v44, 0xbfb8aa3b, v35
	v_exp_f32_e32 v44, v44
	s_nop 0
	v_add_f32_e32 v44, 1.0, v44
	v_rcp_f32_e32 v51, v44
	s_nop 0
	v_pk_mul_f32 v[34:35], v[50:51], v[34:35]
	s_nop 0
	v_pk_mul_f32 v[34:35], v[34:35], v[38:39]
	v_lshlrev_b32_e32 v38, 16, v193
	v_cvt_pk_bf16_f32 v34, v34, v35
	v_mul_f32_e32 v35, 0xbfb8aa3b, v38
	v_exp_f32_e32 v35, v35
	v_and_b32_e32 v39, 0xffff0000, v193
	v_add_f32_e32 v35, 1.0, v35
	v_rcp_f32_e32 v44, v35
	v_mul_f32_e32 v35, 0xbfb8aa3b, v39
	v_exp_f32_e32 v35, v35
	s_nop 0
	v_add_f32_e32 v35, 1.0, v35
	v_rcp_f32_e32 v45, v35
	s_nop 0
	v_pk_mul_f32 v[38:39], v[44:45], v[38:39]
	s_nop 0
	v_pk_mul_f32 v[38:39], v[38:39], v[40:41]
	s_nop 0
	v_cvt_pk_bf16_f32 v35, v38, v39
	v_lshlrev_b32_e32 v38, 16, v194
	v_and_b32_e32 v39, 0xffff0000, v194
	v_mul_f32_e32 v40, 0xbfb8aa3b, v38
	v_mul_f32_e32 v41, 0xbfb8aa3b, v39
	v_exp_f32_e32 v40, v40
	v_exp_f32_e32 v41, v41
	v_add_f32_e32 v40, 1.0, v40
	v_add_f32_e32 v41, 1.0, v41
	v_rcp_f32_e32 v40, v40
	v_rcp_f32_e32 v41, v41
	s_nop 0
	v_pk_mul_f32 v[38:39], v[40:41], v[38:39]
	s_nop 0
	v_pk_mul_f32 v[36:37], v[38:39], v[36:37]
	v_lshlrev_b32_e32 v38, 16, v195
	v_cvt_pk_bf16_f32 v36, v36, v37
	v_mul_f32_e32 v37, 0xbfb8aa3b, v38
	v_exp_f32_e32 v37, v37
	v_and_b32_e32 v39, 0xffff0000, v195
	v_add_f32_e32 v37, 1.0, v37
	v_rcp_f32_e32 v40, v37
	v_mul_f32_e32 v37, 0xbfb8aa3b, v39
	v_exp_f32_e32 v37, v37
	s_nop 0
	v_add_f32_e32 v37, 1.0, v37
	v_rcp_f32_e32 v41, v37
	s_nop 0
	v_pk_mul_f32 v[38:39], v[40:41], v[38:39]
	s_nop 0
	v_pk_mul_f32 v[38:39], v[38:39], v[48:49]
	s_nop 0
	v_cvt_pk_bf16_f32 v37, v38, v39
	global_store_dwordx4 v[42:43], v[34:37], off offset:2112
	s_nop 1
	v_add_f32_e32 v34, 0, v55
	v_add_f32_e32 v34, v34, v57
	v_add_f32_e32 v34, v34, v59
	v_add_f32_e32 v34, v34, v61
	v_add_f32_e32 v34, v34, v63
	v_add_f32_e32 v34, v34, v65
	v_add_f32_e32 v34, v34, v67
	v_add_f32_e32 v34, v34, v69
	v_fmamk_f32 v34, v34, 0x3b000000, v172
	v_cmp_gt_f32_e32 vcc, s4, v34
	v_mul_f32_e32 v35, 0x4f800000, v34
	s_nop 0
	v_cndmask_b32_e32 v34, v34, v35, vcc
	v_sqrt_f32_e32 v35, v34
	s_nop 0
	v_add_u32_e32 v36, -1, v35
	v_fma_f32 v37, -v36, v35, v34
	v_cmp_ge_f32_e64 s[0:1], 0, v37
	v_add_u32_e32 v37, 1, v35
	s_nop 0
	v_cndmask_b32_e64 v36, v35, v36, s[0:1]
	v_fma_f32 v35, -v37, v35, v34
	v_cmp_lt_f32_e64 s[0:1], 0, v35
	s_nop 1
	v_cndmask_b32_e64 v35, v36, v37, s[0:1]
	v_mul_f32_e32 v36, 0x37800000, v35
	v_cndmask_b32_e32 v35, v35, v36, vcc
	v_cmp_class_f32_e32 vcc, v34, v173
	s_nop 1
	v_cndmask_b32_e32 v34, v35, v34, vcc
	v_div_scale_f32 v35, s[0:1], v34, v34, 1.0
	v_rcp_f32_e32 v36, v35
	s_nop 0
	v_fma_f32 v37, -v35, v36, 1.0
	v_fmac_f32_e32 v36, v37, v36
	v_div_scale_f32 v37, vcc, 1.0, v34, 1.0
	v_mul_f32_e32 v38, v37, v36
	v_fma_f32 v39, -v35, v38, v37
	v_fmac_f32_e32 v38, v39, v36
	v_fma_f32 v35, -v35, v38, v37
	v_div_fmas_f32 v35, v35, v36, v38
	v_div_fixup_f32 v38, v35, v34, 1.0
	v_or_b32_e32 v34, 0x70, v150
	v_ashrrev_i32_e32 v35, 31, v34
	v_lshlrev_b64 v[36:37], 9, v[34:35]
	v_lshl_add_u64 v[36:37], s[38:39], 0, v[36:37]
	v_mad_i64_i32 v[34:35], s[0:1], v34, s2, v[152:153]
	v_lshl_add_u64 v[42:43], v[36:37], 0, v[154:155]
	v_lshl_add_u64 v[40:41], v[34:35], 0, s[18:19]
	v_pk_mul_f32 v[14:15], v[14:15], v[38:39] op_sel_hi:[1,0]
	v_pk_mul_f32 v[10:11], v[10:11], v[38:39] op_sel_hi:[1,0]
	v_pk_mul_f32 v[16:17], v[16:17], v[38:39] op_sel_hi:[1,0]
	v_pk_mul_f32 v[14:15], v[30:31], v[14:15]
	v_pk_mul_f32 v[12:13], v[12:13], v[38:39] op_sel_hi:[1,0]
	v_pk_mul_f32 v[10:11], v[26:27], v[10:11]
	v_pk_mul_f32 v[16:17], v[32:33], v[16:17]
	v_pk_mul_f32 v[12:13], v[28:29], v[12:13]
	v_cndmask_b32_e64 v26, v15, v11, s[36:37]
	ds_swizzle_b32 v28, v26 offset:swizzle(SWAP,16)
	v_cndmask_b32_e64 v26, v16, v12, s[36:37]
	v_cndmask_b32_e64 v0, v14, v10, s[36:37]
	ds_swizzle_b32 v26, v26 offset:swizzle(SWAP,16)
	ds_swizzle_b32 v0, v0 offset:swizzle(SWAP,16)
	v_cndmask_b32_e64 v27, v17, v13, s[36:37]
	ds_swizzle_b32 v27, v27 offset:swizzle(SWAP,16)
	s_waitcnt lgkmcnt(3)
	v_cndmask_b32_e64 v15, v28, v15, s[36:37]
	s_waitcnt lgkmcnt(2)
	v_cndmask_b32_e64 v16, v26, v16, s[36:37]
	v_cndmask_b32_e64 v26, v12, v26, s[36:37]
	s_waitcnt lgkmcnt(1)
	v_cndmask_b32_e64 v14, v0, v14, s[36:37]
	v_cndmask_b32_e64 v10, v10, v0, s[36:37]
	s_waitcnt lgkmcnt(0)
	v_cndmask_b32_e64 v17, v27, v17, s[36:37]
	v_cndmask_b32_e64 v27, v13, v27, s[36:37]
	v_cndmask_b32_e64 v11, v11, v28, s[36:37]
	v_pk_mul_f32 v[6:7], v[6:7], v[38:39] op_sel_hi:[1,0]
	v_pk_mul_f32 v[2:3], v[2:3], v[38:39] op_sel_hi:[1,0]
	v_pk_mul_f32 v[8:9], v[8:9], v[38:39] op_sel_hi:[1,0]
	v_pk_mul_f32 v[6:7], v[22:23], v[6:7]
	v_pk_mul_f32 v[4:5], v[4:5], v[38:39] op_sel_hi:[1,0]
	v_pk_mul_f32 v[2:3], v[18:19], v[2:3]
	v_pk_mul_f32 v[8:9], v[24:25], v[8:9]
	v_pk_mul_f32 v[4:5], v[20:21], v[4:5]
	v_readlane_b32 s0, v254, 19
	s_add_i32 s14, s14, s0
	v_readlane_b32 s0, v252, 13
	v_readlane_b32 s1, v252, 14
	s_add_u32 s48, s48, s0
	s_addc_u32 s49, s49, s1
	s_cmpk_gt_i32 s15, 0xff
	s_waitcnt vmcnt(8)
	v_lshlrev_b32_e32 v12, 16, v196
	v_mul_f32_e32 v0, 0xbfb8aa3b, v12
	v_exp_f32_e32 v0, v0
	v_and_b32_e32 v13, 0xffff0000, v196
	v_add_f32_e32 v0, 1.0, v0
	v_rcp_f32_e32 v28, v0
	v_mul_f32_e32 v0, 0xbfb8aa3b, v13
	v_exp_f32_e32 v0, v0
	s_nop 0
	v_add_f32_e32 v0, 1.0, v0
	v_rcp_f32_e32 v29, v0
	s_nop 0
	v_pk_mul_f32 v[12:13], v[28:29], v[12:13]
	s_nop 0
	v_pk_mul_f32 v[12:13], v[12:13], v[14:15]
	v_lshlrev_b32_e32 v14, 16, v197
	v_mul_f32_e32 v0, 0xbfb8aa3b, v14
	v_exp_f32_e32 v0, v0
	v_and_b32_e32 v15, 0xffff0000, v197
	v_cvt_pk_bf16_f32 v12, v12, v13
	v_add_f32_e32 v0, 1.0, v0
	v_rcp_f32_e32 v28, v0
	v_mul_f32_e32 v0, 0xbfb8aa3b, v15
	v_exp_f32_e32 v0, v0
	s_nop 0
	v_add_f32_e32 v0, 1.0, v0
	v_rcp_f32_e32 v29, v0
	s_nop 0
	v_pk_mul_f32 v[14:15], v[28:29], v[14:15]
	s_nop 0
	v_pk_mul_f32 v[14:15], v[14:15], v[16:17]
	s_nop 0
	v_cvt_pk_bf16_f32 v13, v14, v15
	v_lshlrev_b32_e32 v14, 16, v198
	v_mul_f32_e32 v0, 0xbfb8aa3b, v14
	v_exp_f32_e32 v0, v0
	v_and_b32_e32 v15, 0xffff0000, v198
	v_add_f32_e32 v0, 1.0, v0
	v_rcp_f32_e32 v16, v0
	v_mul_f32_e32 v0, 0xbfb8aa3b, v15
	v_exp_f32_e32 v0, v0
	s_nop 0
	v_add_f32_e32 v0, 1.0, v0
	v_rcp_f32_e32 v17, v0
	s_nop 0
	v_pk_mul_f32 v[14:15], v[16:17], v[14:15]
	s_nop 0
	v_pk_mul_f32 v[10:11], v[14:15], v[10:11]
	s_nop 0
	v_cvt_pk_bf16_f32 v14, v10, v11
	v_lshlrev_b32_e32 v10, 16, v199
	v_mul_f32_e32 v0, 0xbfb8aa3b, v10
	v_exp_f32_e32 v0, v0
	v_and_b32_e32 v11, 0xffff0000, v199
	v_add_f32_e32 v0, 1.0, v0
	v_rcp_f32_e32 v16, v0
	v_mul_f32_e32 v0, 0xbfb8aa3b, v11
	v_exp_f32_e32 v0, v0
	s_nop 0
	v_add_f32_e32 v0, 1.0, v0
	v_rcp_f32_e32 v17, v0
	v_cndmask_b32_e64 v0, v6, v2, s[36:37]
	ds_swizzle_b32 v0, v0 offset:swizzle(SWAP,16)
	v_pk_mul_f32 v[10:11], v[16:17], v[10:11]
	s_nop 0
	v_pk_mul_f32 v[10:11], v[10:11], v[26:27]
	v_cndmask_b32_e64 v16, v7, v3, s[36:37]
	v_cvt_pk_bf16_f32 v15, v10, v11
	v_lshl_add_u64 v[10:11], v[40:41], 0, v[138:139]
	global_store_dwordx4 v[10:11], v[12:15], off offset:2048
	ds_swizzle_b32 v18, v16 offset:swizzle(SWAP,16)
	v_cndmask_b32_e64 v16, v8, v4, s[36:37]
	ds_swizzle_b32 v16, v16 offset:swizzle(SWAP,16)
	v_cndmask_b32_e64 v17, v9, v5, s[36:37]
	ds_swizzle_b32 v17, v17 offset:swizzle(SWAP,16)
	s_waitcnt lgkmcnt(3)
	v_cndmask_b32_e64 v6, v0, v6, s[36:37]
	s_waitcnt lgkmcnt(2)
	v_cndmask_b32_e64 v7, v18, v7, s[36:37]
	s_waitcnt lgkmcnt(1)
	v_cndmask_b32_e64 v8, v16, v8, s[36:37]
	v_cndmask_b32_e64 v16, v4, v16, s[36:37]
	v_cndmask_b32_e64 v4, v2, v0, s[36:37]
	s_waitcnt lgkmcnt(0)
	v_cndmask_b32_e64 v9, v17, v9, s[36:37]
	v_cndmask_b32_e64 v17, v5, v17, s[36:37]
	v_cndmask_b32_e64 v5, v3, v18, s[36:37]
	s_waitcnt vmcnt(8)
	v_lshlrev_b32_e32 v2, 16, v200
	v_mul_f32_e32 v0, 0xbfb8aa3b, v2
	v_exp_f32_e32 v0, v0
	v_and_b32_e32 v3, 0xffff0000, v200
	v_add_f32_e32 v0, 1.0, v0
	v_rcp_f32_e32 v18, v0
	v_mul_f32_e32 v0, 0xbfb8aa3b, v3
	v_exp_f32_e32 v0, v0
	s_nop 0
	v_add_f32_e32 v0, 1.0, v0
	v_rcp_f32_e32 v19, v0
	s_nop 0
	v_pk_mul_f32 v[2:3], v[18:19], v[2:3]
	s_nop 0
	v_pk_mul_f32 v[2:3], v[2:3], v[6:7]
	v_lshlrev_b32_e32 v6, 16, v201
	v_mul_f32_e32 v0, 0xbfb8aa3b, v6
	v_exp_f32_e32 v0, v0
	v_and_b32_e32 v7, 0xffff0000, v201
	v_cvt_pk_bf16_f32 v2, v2, v3
	v_add_f32_e32 v0, 1.0, v0
	v_rcp_f32_e32 v12, v0
	v_mul_f32_e32 v0, 0xbfb8aa3b, v7
	v_exp_f32_e32 v0, v0
	s_nop 0
	v_add_f32_e32 v0, 1.0, v0
	v_rcp_f32_e32 v13, v0
	s_nop 0
	v_pk_mul_f32 v[6:7], v[12:13], v[6:7]
	s_nop 0
	v_pk_mul_f32 v[6:7], v[6:7], v[8:9]
	s_nop 0
	v_cvt_pk_bf16_f32 v3, v6, v7
	v_lshlrev_b32_e32 v6, 16, v202
	v_mul_f32_e32 v0, 0xbfb8aa3b, v6
	v_exp_f32_e32 v0, v0
	v_and_b32_e32 v7, 0xffff0000, v202
	v_add_f32_e32 v0, 1.0, v0
	v_rcp_f32_e32 v8, v0
	v_mul_f32_e32 v0, 0xbfb8aa3b, v7
	v_exp_f32_e32 v0, v0
	s_nop 0
	v_add_f32_e32 v0, 1.0, v0
	v_rcp_f32_e32 v9, v0
	s_nop 0
	v_pk_mul_f32 v[6:7], v[8:9], v[6:7]
	s_nop 0
	v_pk_mul_f32 v[4:5], v[6:7], v[4:5]
	v_lshlrev_b32_e32 v6, 16, v203
	v_mul_f32_e32 v0, 0xbfb8aa3b, v6
	v_exp_f32_e32 v0, v0
	v_and_b32_e32 v7, 0xffff0000, v203
	v_cvt_pk_bf16_f32 v4, v4, v5
	v_add_f32_e32 v0, 1.0, v0
	v_rcp_f32_e32 v8, v0
	v_mul_f32_e32 v0, 0xbfb8aa3b, v7
	v_exp_f32_e32 v0, v0
	s_nop 0
	v_add_f32_e32 v0, 1.0, v0
	v_rcp_f32_e32 v9, v0
	s_nop 0
	v_pk_mul_f32 v[6:7], v[8:9], v[6:7]
	s_nop 0
	v_pk_mul_f32 v[6:7], v[6:7], v[16:17]
	s_nop 0
	v_cvt_pk_bf16_f32 v5, v6, v7
	global_store_dwordx4 v[10:11], v[2:5], off offset:2112
	s_cbranch_scc1 .LBB0_516
